# v44: v43 + P7 merge epilogue gate loads all issued before first wait + skinny epilogue row sums via permlane swaps
# speedup vs baseline: 1.0013x; 1.0002x over previous
; #define SK_LOAD(b_, s0_) do { _Pragma("unroll") for (int u = 0; u < UB; ++u) if ((s0_) + u < STEPS) { af[b_][u] = *(const bf16x8*)(ap + ((s0_) + u) * 32); \
;                 _Pragma("unroll") for (int nt = 0; nt < 4; ++nt) wf[b_][u][nt] = *(const bf16x8*)(wp + (size_t)(16 * nt) * ldb + ((s0_) + u) * 32); } } while (0)
; #define SK_MMA(b_, s0_) do { _Pragma("unroll") for (int u = 0; u < UB; ++u) if ((s0_) + u < STEPS) { const bf16x8 afp = sk_perm(af[b_][u], pidx); \
;                 _Pragma("unroll") for (int nt = 0; nt < 4; ++nt) acc[p][nt] = __builtin_amdgcn_mfma_f32_16x16x32_bf16(sk_perm(wf[b_][u][nt], pidx), afp, acc[p][nt], 0, 0, 0); } } while (0)
; template <int NPARTS, int STEPS  , bool FINAL, class Epi> ...
;     ...
;             const bf16_t* wp = Bt + (size_t)(64 * cg + (lane >> 2)) * ldb + p * koff + w * (STEPS * 32) + 8 * (lane & 3);
;             const bf16_t* ap = A + (size_t)(MP + 16 * rg + (lane >> 2)) * lda + p * koff + w * (STEPS * 32) + 8 * (lane & 3);
;             constexpr int NB = (STEPS + UB - 1) / UB;
;             bf16x8 af[2][UB], wf[2][UB][4];
;     ...
;             SK_LOAD(0, 0);
; #pragma unroll
;             for (int b = 0; b < NB; ++b) {
;                 if (b + 1 < NB) { if ((b & 1) == 0) SK_LOAD(1, (b + 1) * UB); else SK_LOAD(0, (b + 1) * UB); }
;                 if ((b & 1) == 0) SK_MMA(0, b * UB); else SK_MMA(1, b * UB);
;             }
.LBB0_648:
	global_load_dwordx4 v[144:147], v[64:65], off
	global_load_dwordx4 v[148:151], v[66:67], off
	global_load_dwordx4 v[152:155], v[68:69], off
	global_load_dwordx4 v[156:159], v[70:71], off
	global_load_dwordx4 v[160:163], v[64:65], off offset:64
	global_load_dwordx4 v[58:61], v[72:73], off
	s_and_b32 s28, s25, -16
	v_add_u32_e32 v2, s28, v139
	v_mad_i64_i32 v[134:135], s[20:21], v2, s24, v[62:63]
	global_load_dwordx4 v[164:167], v[134:135], off
	global_load_dwordx4 v[54:57], v[74:75], off
	global_load_dwordx4 v[50:53], v[76:77], off
	global_load_dwordx4 v[46:49], v[134:135], off offset:64
	global_load_dwordx4 v[42:45], v[64:65], off offset:128
	global_load_dwordx4 v[38:41], v[78:79], off
	global_load_dwordx4 v[34:37], v[134:135], off offset:128
	global_load_dwordx4 v[30:33], v[80:81], off
	global_load_dwordx4 v[26:29], v[82:83], off
	global_load_dwordx4 v[22:25], v[64:65], off offset:192
	global_load_dwordx4 v[18:21], v[84:85], off
	global_load_dwordx4 v[14:17], v[86:87], off
	global_load_dwordx4 v[10:13], v[88:89], off
	global_load_dwordx4 v[6:9], v[64:65], off offset:256
	global_load_dwordx4 v[2:5], v[64:65], off offset:640
	global_load_dwordx4 v[168:171], v[134:135], off offset:192
	global_load_dwordx4 v[172:175], v[134:135], off offset:256
	s_andn2_b64 vcc, exec, s[8:9]
	s_waitcnt vmcnt(16)
	ds_bpermute_b32 v164, v136, v164
	ds_bpermute_b32 v165, v136, v165
	ds_bpermute_b32 v166, v136, v166
	ds_bpermute_b32 v167, v136, v167
	s_waitcnt vmcnt(15)
	ds_bpermute_b32 v54, v136, v54
	ds_bpermute_b32 v55, v136, v55
	ds_bpermute_b32 v144, v136, v144
	ds_bpermute_b32 v145, v136, v145
	ds_bpermute_b32 v146, v136, v146
	ds_bpermute_b32 v147, v136, v147
	ds_bpermute_b32 v148, v136, v148
	ds_bpermute_b32 v149, v136, v149
	ds_bpermute_b32 v150, v136, v150
	ds_bpermute_b32 v151, v136, v151
	ds_bpermute_b32 v152, v136, v152
	ds_bpermute_b32 v153, v136, v153
	ds_bpermute_b32 v154, v136, v154
	ds_bpermute_b32 v155, v136, v155
	ds_bpermute_b32 v156, v136, v156
	ds_bpermute_b32 v157, v136, v157
	ds_bpermute_b32 v158, v136, v158
	ds_bpermute_b32 v159, v136, v159
	ds_bpermute_b32 v160, v136, v160
	ds_bpermute_b32 v161, v136, v161
	ds_bpermute_b32 v162, v136, v162
	ds_bpermute_b32 v163, v136, v163
	ds_bpermute_b32 v58, v136, v58
	ds_bpermute_b32 v59, v136, v59
	ds_bpermute_b32 v60, v136, v60
	ds_bpermute_b32 v61, v136, v61
	ds_bpermute_b32 v56, v136, v56
	ds_bpermute_b32 v57, v136, v57
	s_waitcnt vmcnt(14)
	ds_bpermute_b32 v50, v136, v50
	ds_bpermute_b32 v51, v136, v51
	ds_bpermute_b32 v52, v136, v52
	ds_bpermute_b32 v53, v136, v53
	s_waitcnt vmcnt(13)
	ds_bpermute_b32 v46, v136, v46
	ds_bpermute_b32 v47, v136, v47
	ds_bpermute_b32 v48, v136, v48
	ds_bpermute_b32 v49, v136, v49
	s_waitcnt lgkmcnt(14)
	v_mfma_f32_16x16x32_bf16 v[144:147], v[144:147], v[164:167], 0
	s_waitcnt vmcnt(9)
	ds_bpermute_b32 v30, v136, v30
	ds_bpermute_b32 v31, v136, v31
	ds_bpermute_b32 v32, v136, v32
	v_mfma_f32_16x16x32_bf16 v[148:151], v[148:151], v[164:167], 0
	ds_bpermute_b32 v33, v136, v33
	ds_bpermute_b32 v34, v136, v34
	ds_bpermute_b32 v35, v136, v35
	v_mfma_f32_16x16x32_bf16 v[152:155], v[152:155], v[164:167], 0
	ds_bpermute_b32 v36, v136, v36
	ds_bpermute_b32 v37, v136, v37
	s_waitcnt vmcnt(8)
	ds_bpermute_b32 v26, v136, v26
	v_mfma_f32_16x16x32_bf16 v[156:159], v[156:159], v[164:167], 0
	ds_bpermute_b32 v27, v136, v27
	ds_bpermute_b32 v28, v136, v28
	ds_bpermute_b32 v29, v136, v29
	s_waitcnt lgkmcnt(12)
	v_mfma_f32_16x16x32_bf16 v[144:147], v[160:163], v[46:49], v[144:147]
	ds_bpermute_b32 v42, v136, v42
	ds_bpermute_b32 v43, v136, v43
	ds_bpermute_b32 v44, v136, v44
	v_mfma_f32_16x16x32_bf16 v[58:61], v[58:61], v[46:49], v[148:151]
	ds_bpermute_b32 v45, v136, v45
	ds_bpermute_b32 v38, v136, v38
	ds_bpermute_b32 v39, v136, v39
	v_mfma_f32_16x16x32_bf16 v[54:57], v[54:57], v[46:49], v[152:155]
	ds_bpermute_b32 v40, v136, v40
	ds_bpermute_b32 v41, v136, v41
	s_waitcnt vmcnt(7)
	ds_bpermute_b32 v22, v136, v22
	v_mfma_f32_16x16x32_bf16 v[46:49], v[50:53], v[46:49], v[156:159]
	global_load_dwordx4 v[50:53], v[90:91], off
	ds_bpermute_b32 v23, v136, v23
	ds_bpermute_b32 v24, v136, v24
	s_waitcnt lgkmcnt(14)
	v_mfma_f32_16x16x32_bf16 v[30:33], v[30:33], v[34:37], v[54:57]
	ds_bpermute_b32 v25, v136, v25
	s_waitcnt vmcnt(7)
	ds_bpermute_b32 v18, v136, v18
	ds_bpermute_b32 v19, v136, v19
	global_load_dwordx4 v[54:57], v[92:93], off
	s_waitcnt lgkmcnt(14)
	v_mfma_f32_16x16x32_bf16 v[26:29], v[26:29], v[34:37], v[46:49]
	ds_bpermute_b32 v20, v136, v20
	ds_bpermute_b32 v21, v136, v21
	s_waitcnt vmcnt(7)
	ds_bpermute_b32 v14, v136, v14
	global_load_dwordx4 v[46:49], v[94:95], off
	s_waitcnt lgkmcnt(13)
	v_mfma_f32_16x16x32_bf16 v[42:45], v[42:45], v[34:37], v[144:147]
	ds_bpermute_b32 v15, v136, v15
	ds_bpermute_b32 v16, v136, v16
	ds_bpermute_b32 v17, v136, v17
	s_waitcnt lgkmcnt(12)
	v_mfma_f32_16x16x32_bf16 v[38:41], v[38:41], v[34:37], v[58:61]
	s_waitcnt vmcnt(4)
	ds_bpermute_b32 v34, v136, v168
	ds_bpermute_b32 v35, v136, v169
	ds_bpermute_b32 v36, v136, v170
	ds_bpermute_b32 v37, v136, v171
	s_waitcnt lgkmcnt(0)
	v_mfma_f32_16x16x32_bf16 v[22:25], v[22:25], v[34:37], v[42:45]
	s_nop 2
	global_load_dwordx4 v[42:45], v[134:135], off offset:320
	global_load_dwordx4 v[58:61], v[64:65], off offset:320
	ds_bpermute_b32 v10, v136, v10
	ds_bpermute_b32 v11, v136, v11
	v_mfma_f32_16x16x32_bf16 v[18:21], v[18:21], v[34:37], v[38:41]
	ds_bpermute_b32 v12, v136, v12
	ds_bpermute_b32 v13, v136, v13
	ds_bpermute_b32 v6, v136, v6
	global_load_dwordx4 v[38:41], v[96:97], off
	v_mfma_f32_16x16x32_bf16 v[14:17], v[14:17], v[34:37], v[30:33]
	ds_bpermute_b32 v7, v136, v7
	ds_bpermute_b32 v8, v136, v8
	ds_bpermute_b32 v9, v136, v9
	global_load_dwordx4 v[30:33], v[98:99], off
	s_waitcnt lgkmcnt(4)
; #define SK_LOAD(b_, s0_) do { _Pragma("unroll") for (int u = 0; u < UB; ++u) if ((s0_) + u < STEPS) { af[b_][u] = *(const bf16x8*)(ap + ((s0_) + u) * 32); \
;                 _Pragma("unroll") for (int nt = 0; nt < 4; ++nt) wf[b_][u][nt] = *(const bf16x8*)(wp + (size_t)(16 * nt) * ldb + ((s0_) + u) * 32); } } while (0)
; #define SK_MMA(b_, s0_) do { _Pragma("unroll") for (int u = 0; u < UB; ++u) if ((s0_) + u < STEPS) { const bf16x8 afp = sk_perm(af[b_][u], pidx); \
;                 _Pragma("unroll") for (int nt = 0; nt < 4; ++nt) acc[p][nt] = __builtin_amdgcn_mfma_f32_16x16x32_bf16(sk_perm(wf[b_][u][nt], pidx), afp, acc[p][nt], 0, 0, 0); } } while (0)
; template <int NPARTS, int STEPS  , bool FINAL, class Epi> ...
;     ...
;             const bf16_t* wp = Bt + (size_t)(64 * cg + (lane >> 2)) * ldb + p * koff + w * (STEPS * 32) + 8 * (lane & 3);
;             const bf16_t* ap = A + (size_t)(MP + 16 * rg + (lane >> 2)) * lda + p * koff + w * (STEPS * 32) + 8 * (lane & 3);
;             constexpr int NB = (STEPS + UB - 1) / UB;
;             bf16x8 af[2][UB], wf[2][UB][4];
;     ...
;             SK_LOAD(0, 0);
; #pragma unroll
;             for (int b = 0; b < NB; ++b) {
;                 if (b + 1 < NB) { if ((b & 1) == 0) SK_LOAD(1, (b + 1) * UB); else SK_LOAD(0, (b + 1) * UB); }
;                 if ((b & 1) == 0) SK_MMA(0, b * UB); else SK_MMA(1, b * UB);
;             }
	v_mfma_f32_16x16x32_bf16 v[10:13], v[10:13], v[34:37], v[26:29]
	global_load_dwordx4 v[34:37], v[100:101], off
	ds_bpermute_b32 v2, v136, v2
	s_waitcnt vmcnt(8)
	ds_bpermute_b32 v26, v136, v172
	ds_bpermute_b32 v27, v136, v173
	ds_bpermute_b32 v28, v136, v174
	ds_bpermute_b32 v29, v136, v175
	s_waitcnt lgkmcnt(0)
	v_mfma_f32_16x16x32_bf16 v[6:9], v[6:9], v[26:29], v[22:25]
	ds_bpermute_b32 v3, v136, v3
	ds_bpermute_b32 v4, v136, v4
	ds_bpermute_b32 v5, v136, v5
	s_waitcnt vmcnt(7)
	ds_bpermute_b32 v22, v136, v50
	ds_bpermute_b32 v23, v136, v51
	ds_bpermute_b32 v24, v136, v52
	ds_bpermute_b32 v25, v136, v53
	global_load_dwordx4 v[50:53], v[134:135], off offset:384
	global_load_dwordx4 v[144:147], v[64:65], off offset:384
	s_waitcnt lgkmcnt(0)
	v_mfma_f32_16x16x32_bf16 v[18:21], v[22:25], v[26:29], v[18:21]
	s_waitcnt vmcnt(8)
	ds_bpermute_b32 v22, v136, v54
	ds_bpermute_b32 v23, v136, v55
	ds_bpermute_b32 v24, v136, v56
	ds_bpermute_b32 v25, v136, v57
	global_load_dwordx4 v[54:57], v[102:103], off
	s_waitcnt lgkmcnt(0)
	v_mfma_f32_16x16x32_bf16 v[14:17], v[22:25], v[26:29], v[14:17]
	s_waitcnt vmcnt(8)
	ds_bpermute_b32 v22, v136, v46
	ds_bpermute_b32 v23, v136, v47
	ds_bpermute_b32 v24, v136, v48
	ds_bpermute_b32 v25, v136, v49
	global_load_dwordx4 v[46:49], v[104:105], off
	s_waitcnt lgkmcnt(0)
	v_mfma_f32_16x16x32_bf16 v[10:13], v[22:25], v[26:29], v[10:13]
	s_waitcnt vmcnt(8)
	ds_bpermute_b32 v26, v136, v42
	ds_bpermute_b32 v27, v136, v43
	ds_bpermute_b32 v28, v136, v44
	ds_bpermute_b32 v29, v136, v45
	global_load_dwordx4 v[42:45], v[106:107], off
	s_waitcnt vmcnt(8)
	ds_bpermute_b32 v22, v136, v58
	ds_bpermute_b32 v23, v136, v59
	ds_bpermute_b32 v24, v136, v60
	ds_bpermute_b32 v25, v136, v61
	s_waitcnt lgkmcnt(0)
	v_mfma_f32_16x16x32_bf16 v[6:9], v[22:25], v[26:29], v[6:9]
	s_waitcnt vmcnt(7)
	ds_bpermute_b32 v22, v136, v38
	ds_bpermute_b32 v23, v136, v39
	ds_bpermute_b32 v24, v136, v40
	ds_bpermute_b32 v25, v136, v41
	global_load_dwordx4 v[38:41], v[134:135], off offset:448
	global_load_dwordx4 v[58:61], v[64:65], off offset:448
	s_waitcnt lgkmcnt(0)
	v_mfma_f32_16x16x32_bf16 v[18:21], v[22:25], v[26:29], v[18:21]
	s_waitcnt vmcnt(8)
	ds_bpermute_b32 v22, v136, v30
	ds_bpermute_b32 v23, v136, v31
	ds_bpermute_b32 v24, v136, v32
	ds_bpermute_b32 v25, v136, v33
	global_load_dwordx4 v[30:33], v[108:109], off
	s_waitcnt lgkmcnt(0)
	v_mfma_f32_16x16x32_bf16 v[14:17], v[22:25], v[26:29], v[14:17]
	s_waitcnt vmcnt(8)
	ds_bpermute_b32 v22, v136, v34
	ds_bpermute_b32 v23, v136, v35
	ds_bpermute_b32 v24, v136, v36
	ds_bpermute_b32 v25, v136, v37
	global_load_dwordx4 v[34:37], v[110:111], off
	s_waitcnt lgkmcnt(0)
	v_mfma_f32_16x16x32_bf16 v[10:13], v[22:25], v[26:29], v[10:13]
	s_waitcnt vmcnt(7)
	ds_bpermute_b32 v22, v136, v144
	ds_bpermute_b32 v23, v136, v145
	ds_bpermute_b32 v24, v136, v146
	ds_bpermute_b32 v25, v136, v147
	ds_bpermute_b32 v26, v136, v50
	ds_bpermute_b32 v27, v136, v51
	ds_bpermute_b32 v28, v136, v52
	ds_bpermute_b32 v29, v136, v53
	global_load_dwordx4 v[50:53], v[112:113], off
	s_waitcnt lgkmcnt(0)
	v_mfma_f32_16x16x32_bf16 v[6:9], v[22:25], v[26:29], v[6:9]
	s_waitcnt vmcnt(7)
	ds_bpermute_b32 v22, v136, v54
	ds_bpermute_b32 v23, v136, v55
	ds_bpermute_b32 v24, v136, v56
	ds_bpermute_b32 v25, v136, v57
	global_load_dwordx4 v[54:57], v[134:135], off offset:512
	global_load_dwordx4 v[144:147], v[64:65], off offset:512
	s_waitcnt lgkmcnt(0)
	v_mfma_f32_16x16x32_bf16 v[18:21], v[22:25], v[26:29], v[18:21]
	s_waitcnt vmcnt(8)
	ds_bpermute_b32 v22, v136, v46
	ds_bpermute_b32 v23, v136, v47
	ds_bpermute_b32 v24, v136, v48
	ds_bpermute_b32 v25, v136, v49
	global_load_dwordx4 v[46:49], v[114:115], off
	s_waitcnt lgkmcnt(0)
	v_mfma_f32_16x16x32_bf16 v[14:17], v[22:25], v[26:29], v[14:17]
	s_waitcnt vmcnt(8)
	ds_bpermute_b32 v22, v136, v42
	ds_bpermute_b32 v23, v136, v43
	ds_bpermute_b32 v24, v136, v44
	ds_bpermute_b32 v25, v136, v45
	global_load_dwordx4 v[42:45], v[116:117], off
	s_waitcnt lgkmcnt(0)
	v_mfma_f32_16x16x32_bf16 v[10:13], v[22:25], v[26:29], v[10:13]
	s_waitcnt vmcnt(8)
	ds_bpermute_b32 v26, v136, v38
	ds_bpermute_b32 v27, v136, v39
	ds_bpermute_b32 v28, v136, v40
	ds_bpermute_b32 v29, v136, v41
	global_load_dwordx4 v[38:41], v[118:119], off
	s_waitcnt vmcnt(8)
	ds_bpermute_b32 v22, v136, v58
	ds_bpermute_b32 v23, v136, v59
	ds_bpermute_b32 v24, v136, v60
	ds_bpermute_b32 v25, v136, v61
	s_waitcnt lgkmcnt(0)
	v_mfma_f32_16x16x32_bf16 v[6:9], v[22:25], v[26:29], v[6:9]
	s_waitcnt vmcnt(7)
	ds_bpermute_b32 v22, v136, v30
	ds_bpermute_b32 v23, v136, v31
	ds_bpermute_b32 v24, v136, v32
	ds_bpermute_b32 v25, v136, v33
	global_load_dwordx4 v[30:33], v[134:135], off offset:576
	global_load_dwordx4 v[58:61], v[64:65], off offset:576
	s_waitcnt lgkmcnt(0)
	v_mfma_f32_16x16x32_bf16 v[18:21], v[22:25], v[26:29], v[18:21]
	s_waitcnt vmcnt(8)
	ds_bpermute_b32 v22, v136, v34
	ds_bpermute_b32 v23, v136, v35
	ds_bpermute_b32 v24, v136, v36
	ds_bpermute_b32 v25, v136, v37
	global_load_dwordx4 v[34:37], v[120:121], off
	s_waitcnt lgkmcnt(0)
	v_mfma_f32_16x16x32_bf16 v[14:17], v[22:25], v[26:29], v[14:17]
	s_waitcnt vmcnt(8)
	ds_bpermute_b32 v22, v136, v50
	ds_bpermute_b32 v23, v136, v51
	ds_bpermute_b32 v24, v136, v52
	ds_bpermute_b32 v25, v136, v53
	global_load_dwordx4 v[50:53], v[122:123], off
	s_waitcnt lgkmcnt(0)
	v_mfma_f32_16x16x32_bf16 v[10:13], v[22:25], v[26:29], v[10:13]
	s_waitcnt vmcnt(7)
	ds_bpermute_b32 v22, v136, v144
	ds_bpermute_b32 v23, v136, v145
	ds_bpermute_b32 v24, v136, v146
	ds_bpermute_b32 v25, v136, v147
	ds_bpermute_b32 v26, v136, v54
	ds_bpermute_b32 v27, v136, v55
	ds_bpermute_b32 v28, v136, v56
	ds_bpermute_b32 v29, v136, v57
	global_load_dwordx4 v[54:57], v[124:125], off
	s_waitcnt lgkmcnt(0)
; #define SK_LOAD(b_, s0_) do { _Pragma("unroll") for (int u = 0; u < UB; ++u) if ((s0_) + u < STEPS) { af[b_][u] = *(const bf16x8*)(ap + ((s0_) + u) * 32); \
;                 _Pragma("unroll") for (int nt = 0; nt < 4; ++nt) wf[b_][u][nt] = *(const bf16x8*)(wp + (size_t)(16 * nt) * ldb + ((s0_) + u) * 32); } } while (0)
; #define SK_MMA(b_, s0_) do { _Pragma("unroll") for (int u = 0; u < UB; ++u) if ((s0_) + u < STEPS) { const bf16x8 afp = sk_perm(af[b_][u], pidx); \
;                 _Pragma("unroll") for (int nt = 0; nt < 4; ++nt) acc[p][nt] = __builtin_amdgcn_mfma_f32_16x16x32_bf16(sk_perm(wf[b_][u][nt], pidx), afp, acc[p][nt], 0, 0, 0); } } while (0)
; template <int NPARTS, int STEPS  , bool FINAL, class Epi> ...
;     ...
;             SK_LOAD(0, 0);
; #pragma unroll
;             for (int b = 0; b < NB; ++b) {
;                 if (b + 1 < NB) { if ((b & 1) == 0) SK_LOAD(1, (b + 1) * UB); else SK_LOAD(0, (b + 1) * UB); }
;                 if ((b & 1) == 0) SK_MMA(0, b * UB); else SK_MMA(1, b * UB);
;             }
;     ...
;         }
; #pragma unroll
;         for (int p = 0; p < NPARTS; ++p)
; #pragma unroll
;             for (int nt = 0; nt < 4; ++nt) red[((w * NPARTS + p) * 4 + nt) * 64 + lane] = acc[p][nt];
;         __syncthreads();
;         f32x4 o = (f32x4){0.f, 0.f, 0.f, 0.f};
;         if (w < 4) {
;             f32x4 a2[NPARTS];
; #pragma unroll
;             for (int p = 0; p < NPARTS; ++p) { a2[p] = (f32x4){0.f, 0.f, 0.f, 0.f};
; #pragma unroll
;                 for (int w2 = 0; w2 < 8; ++w2) a2[p] += red[((w2 * NPARTS + p) * 4 + w) * 64 + lane]; }
;             const int row = MP + 16 * rg + fr, c0 = 64 * cg + 16 * w + 4 * fq;
;             o = E(row, c0, a2);
;             float s = (o[0] * o[0] + o[1] * o[1]) + (o[2] * o[2] + o[3] * o[3]);
;             s += __shfl_xor(s, 16); s += __shfl_xor(s, 32);
;             if (fq == 0) sred[w * 16 + fr] = s;
;     __device__ __forceinline__ f32x4 operator()(int row, int c0, const f32x4 (&acc)[1]) const {
;         const size_t off = (size_t)row * D + c0;
;         f32x4 b;
;         if (BASE_BF16) b = unpack4(*(const u32x2*)((const bf16_t*)base + off)); else b = *(const f32x4*)((const float*)base + (off - (size_t)MP * D));
;         const f32x4 v = b + acc[0] * scale;
;         if (OUT_F32) *(f32x4*)(outf + off) = v;
;         if (OUT_BF16) *(u32x2*)(outb + off) = pack4(v);
;         return v;
	v_mfma_f32_16x16x32_bf16 v[6:9], v[22:25], v[26:29], v[6:9]
	s_waitcnt vmcnt(7)
	ds_bpermute_b32 v22, v136, v46
	ds_bpermute_b32 v23, v136, v47
	ds_bpermute_b32 v24, v136, v48
	ds_bpermute_b32 v25, v136, v49
	global_load_dwordx4 v[46:49], v[134:135], off offset:640
	s_waitcnt lgkmcnt(0)
	v_mfma_f32_16x16x32_bf16 v[18:21], v[22:25], v[26:29], v[18:21]
	s_waitcnt vmcnt(7)
	ds_bpermute_b32 v22, v136, v42
	ds_bpermute_b32 v23, v136, v43
	ds_bpermute_b32 v24, v136, v44
	ds_bpermute_b32 v25, v136, v45
	global_load_dwordx4 v[42:45], v[126:127], off
	s_waitcnt lgkmcnt(0)
	v_mfma_f32_16x16x32_bf16 v[14:17], v[22:25], v[26:29], v[14:17]
	s_waitcnt vmcnt(7)
	ds_bpermute_b32 v22, v136, v38
	ds_bpermute_b32 v23, v136, v39
	ds_bpermute_b32 v24, v136, v40
	ds_bpermute_b32 v25, v136, v41
	global_load_dwordx4 v[38:41], v[128:129], off
	s_waitcnt lgkmcnt(0)
	v_mfma_f32_16x16x32_bf16 v[10:13], v[22:25], v[26:29], v[10:13]
	s_waitcnt vmcnt(7)
	ds_bpermute_b32 v26, v136, v30
	ds_bpermute_b32 v27, v136, v31
	ds_bpermute_b32 v28, v136, v32
	ds_bpermute_b32 v29, v136, v33
	global_load_dwordx4 v[30:33], v[130:131], off
	s_waitcnt vmcnt(7)
	ds_bpermute_b32 v22, v136, v58
	ds_bpermute_b32 v23, v136, v59
	ds_bpermute_b32 v24, v136, v60
	ds_bpermute_b32 v25, v136, v61
	s_waitcnt lgkmcnt(0)
	v_mfma_f32_16x16x32_bf16 v[6:9], v[22:25], v[26:29], v[6:9]
	s_waitcnt vmcnt(6)
	ds_bpermute_b32 v22, v136, v34
	ds_bpermute_b32 v23, v136, v35
	ds_bpermute_b32 v24, v136, v36
	ds_bpermute_b32 v25, v136, v37
	s_waitcnt lgkmcnt(0)
	v_mfma_f32_16x16x32_bf16 v[18:21], v[22:25], v[26:29], v[18:21]
	s_waitcnt vmcnt(5)
	ds_bpermute_b32 v22, v136, v50
	ds_bpermute_b32 v23, v136, v51
	ds_bpermute_b32 v24, v136, v52
	ds_bpermute_b32 v25, v136, v53
	s_waitcnt lgkmcnt(0)
	v_mfma_f32_16x16x32_bf16 v[14:17], v[22:25], v[26:29], v[14:17]
	s_waitcnt vmcnt(4)
	ds_bpermute_b32 v22, v136, v54
	ds_bpermute_b32 v23, v136, v55
	ds_bpermute_b32 v24, v136, v56
	ds_bpermute_b32 v25, v136, v57
	s_waitcnt lgkmcnt(0)
	v_mfma_f32_16x16x32_bf16 v[10:13], v[22:25], v[26:29], v[10:13]
	s_waitcnt vmcnt(3)
	ds_bpermute_b32 v22, v136, v46
	ds_bpermute_b32 v23, v136, v47
	ds_bpermute_b32 v24, v136, v48
	ds_bpermute_b32 v25, v136, v49
	s_waitcnt lgkmcnt(0)
	v_mfma_f32_16x16x32_bf16 v[2:5], v[2:5], v[22:25], v[6:9]
	s_waitcnt vmcnt(2)
	s_nop 1
	ds_bpermute_b32 v6, v136, v42
	ds_bpermute_b32 v7, v136, v43
	ds_bpermute_b32 v8, v136, v44
	ds_bpermute_b32 v9, v136, v45
	s_waitcnt lgkmcnt(0)
	v_mfma_f32_16x16x32_bf16 v[6:9], v[6:9], v[22:25], v[18:21]
	s_waitcnt vmcnt(1)
	s_nop 1
	ds_bpermute_b32 v18, v136, v38
	ds_bpermute_b32 v19, v136, v39
	ds_bpermute_b32 v20, v136, v40
	ds_bpermute_b32 v21, v136, v41
	s_waitcnt lgkmcnt(0)
	v_mfma_f32_16x16x32_bf16 v[14:17], v[18:21], v[22:25], v[14:17]
	s_waitcnt vmcnt(0)
	ds_bpermute_b32 v18, v136, v30
	ds_bpermute_b32 v19, v136, v31
	ds_bpermute_b32 v20, v136, v32
	ds_bpermute_b32 v21, v136, v33
	s_waitcnt lgkmcnt(0)
	v_mfma_f32_16x16x32_bf16 v[10:13], v[18:21], v[22:25], v[10:13]
	v_add_u32_e32 v18, s3, v140
	ds_write_b128 v18, v[2:5]
	ds_write_b128 v18, v[6:9] offset:1024
	ds_write_b128 v18, v[14:17] offset:2048
	s_nop 3
	ds_write_b128 v18, v[10:13] offset:3072
	s_waitcnt lgkmcnt(0)
	s_barrier
	s_cbranch_vccnz .LBB0_652
	v_add_u32_e32 v2, s28, v137
	v_ashrrev_i32_e32 v3, 31, v2
	v_lshlrev_b64 v[2:3], 11, v[2:3]
	v_lshl_add_u64 v[34:35], v[132:133], 0, v[2:3]
	global_load_dwordx2 v[36:37], v[34:35], off
	ds_read_b128 v[2:5], v141
	ds_read_b128 v[6:9], v141 offset:4096
	ds_read_b128 v[10:13], v141 offset:8192
	ds_read_b128 v[14:17], v141 offset:12288
	ds_read_b128 v[18:21], v141 offset:16384
	ds_read_b128 v[22:25], v141 offset:20480
	ds_read_b128 v[26:29], v141 offset:24576
	ds_read_b128 v[30:33], v141 offset:28672
	s_waitcnt lgkmcnt(7)
	v_pk_add_f32 v[4:5], v[4:5], 0 op_sel_hi:[1,0]
	v_pk_add_f32 v[2:3], v[2:3], 0 op_sel_hi:[1,0]
	s_waitcnt lgkmcnt(6)
	v_pk_add_f32 v[4:5], v[4:5], v[8:9]
	v_pk_add_f32 v[2:3], v[2:3], v[6:7]
	s_waitcnt lgkmcnt(5)
	v_pk_add_f32 v[4:5], v[4:5], v[12:13]
	v_pk_add_f32 v[2:3], v[2:3], v[10:11]
	s_waitcnt lgkmcnt(4)
	v_pk_add_f32 v[4:5], v[4:5], v[16:17]
	v_pk_add_f32 v[2:3], v[2:3], v[14:15]
	s_waitcnt lgkmcnt(3)
	v_pk_add_f32 v[4:5], v[4:5], v[20:21]
	v_pk_add_f32 v[2:3], v[2:3], v[18:19]
	s_waitcnt lgkmcnt(2)
	v_pk_add_f32 v[4:5], v[4:5], v[24:25]
	v_pk_add_f32 v[2:3], v[2:3], v[22:23]
	s_waitcnt lgkmcnt(1)
	v_pk_add_f32 v[4:5], v[4:5], v[28:29]
	v_pk_add_f32 v[2:3], v[2:3], v[26:27]
	v_and_b32_e32 v39, 64, v143
	s_waitcnt lgkmcnt(0)
	v_pk_add_f32 v[4:5], v[4:5], v[32:33]
	v_pk_add_f32 v[2:3], v[2:3], v[30:31]
	v_xor_b32_e32 v38, 16, v143
	v_add_u32_e32 v39, 64, v39
	v_cmp_lt_i32_e32 vcc, v38, v39
	s_waitcnt vmcnt(0)
	v_lshlrev_b32_e32 v6, 16, v36
	v_and_b32_e32 v7, 0xffff0000, v36
	v_lshlrev_b32_e32 v8, 16, v37
	v_and_b32_e32 v9, 0xffff0000, v37
	v_pk_fma_f32 v[4:5], v[4:5], 0.5, v[8:9] op_sel_hi:[1,0,1]
	v_pk_fma_f32 v[6:7], v[2:3], 0.5, v[6:7] op_sel_hi:[1,0,1]
	v_mul_f32_e32 v3, v5, v5
	v_mul_f32_e32 v2, v7, v7
	v_cndmask_b32_e32 v38, v143, v38, vcc
	v_fmac_f32_e32 v2, v6, v6
	v_fmac_f32_e32 v3, v4, v4
	v_lshlrev_b32_e32 v38, 2, v38
	v_add_f32_e32 v2, v2, v3
	v_mov_b32_e32 v3, v2
	s_nop 1
	v_permlane16_swap_b32_e32 v2, v3
	v_xor_b32_e32 v8, 32, v143
	v_cmp_lt_i32_e32 vcc, v8, v39
	v_cvt_pk_bf16_f32 v6, v6, v7
	v_cvt_pk_bf16_f32 v7, v4, v5
	v_cndmask_b32_e32 v8, v143, v8, vcc
	s_waitcnt lgkmcnt(0)
	v_add_f32_e32 v2, v2, v3
	v_lshlrev_b32_e32 v3, 2, v8
	v_mov_b32_e32 v3, v2
	s_nop 1
	v_permlane32_swap_b32_e32 v2, v3
	global_store_dwordx2 v[34:35], v[6:7], off
	s_and_saveexec_b64 s[20:21], s[4:5]
	s_cbranch_execz .LBB0_651
	s_waitcnt lgkmcnt(0)
	v_add_f32_e32 v2, v2, v3
	ds_write_b32 v142, v2 offset:32768

; #define SK_LOAD(b_, s0_) do { _Pragma("unroll") for (int u = 0; u < UB; ++u) if ((s0_) + u < STEPS) { af[b_][u] = *(const bf16x8*)(ap + ((s0_) + u) * 32); \
;                 _Pragma("unroll") for (int nt = 0; nt < 4; ++nt) wf[b_][u][nt] = *(const bf16x8*)(wp + (size_t)(16 * nt) * ldb + ((s0_) + u) * 32); } } while (0)
; #define SK_MMA(b_, s0_) do { _Pragma("unroll") for (int u = 0; u < UB; ++u) if ((s0_) + u < STEPS) { const bf16x8 afp = sk_perm(af[b_][u], pidx); \
;                 _Pragma("unroll") for (int nt = 0; nt < 4; ++nt) acc[p][nt] = __builtin_amdgcn_mfma_f32_16x16x32_bf16(sk_perm(wf[b_][u][nt], pidx), afp, acc[p][nt], 0, 0, 0); } } while (0)
; template <int NPARTS, int STEPS  , bool FINAL, class Epi> ...
;     ...
;             const bf16_t* wp = Bt + (size_t)(64 * cg + (lane >> 2)) * ldb + p * koff + w * (STEPS * 32) + 8 * (lane & 3);
;             const bf16_t* ap = A + (size_t)(MP + 16 * rg + (lane >> 2)) * lda + p * koff + w * (STEPS * 32) + 8 * (lane & 3);
;             constexpr int NB = (STEPS + UB - 1) / UB;
;             bf16x8 af[2][UB], wf[2][UB][4];
;     ...
;             SK_LOAD(0, 0);
; #pragma unroll
;             for (int b = 0; b < NB; ++b) {
;                 if (b + 1 < NB) { if ((b & 1) == 0) SK_LOAD(1, (b + 1) * UB); else SK_LOAD(0, (b + 1) * UB); }
;                 if ((b & 1) == 0) SK_MMA(0, b * UB); else SK_MMA(1, b * UB);
;             }
.LBB0_704:
	s_and_b32 s8, s20, 15
	s_lshl_b32 s18, s8, 6
	v_or_b32_e32 v2, s18, v77
	v_mul_u32_u24_e32 v2, 0xb00, v2
	v_lshlrev_b32_e32 v58, 1, v2
	v_lshl_add_u64 v[68:69], v[60:61], 0, v[58:59]
	v_add_co_u32_e32 v72, vcc, 0x16000, v68
	s_and_b32 s21, s20, -16
	s_nop 0
	v_addc_co_u32_e32 v73, vcc, 0, v69, vcc
	v_add_u32_e32 v3, s21, v78
	v_add_co_u32_e32 v70, vcc, 0x2c000, v68
	v_mad_i64_i32 v[66:67], s[24:25], v3, s3, v[62:63]
	s_nop 0
	v_addc_co_u32_e32 v71, vcc, 0, v69, vcc
	global_load_dwordx4 v[38:41], v[66:67], off
	global_load_dwordx4 v[84:87], v[66:67], off offset:64
	global_load_dwordx4 v[54:57], v[68:69], off
	global_load_dwordx4 v[22:25], v[66:67], off offset:128
	global_load_dwordx4 v[88:91], v[72:73], off
	global_load_dwordx4 v[92:95], v[68:69], off offset:64
	global_load_dwordx4 v[96:99], v[70:71], off
	v_add_co_u32_e32 v64, vcc, 0x42000, v68
	s_waitcnt vmcnt(6)
	ds_bpermute_b32 v38, v74, v38
	v_addc_co_u32_e32 v65, vcc, 0, v69, vcc
	global_load_dwordx4 v[100:103], v[64:65], off
	global_load_dwordx4 v[50:53], v[72:73], off offset:64
	global_load_dwordx4 v[46:49], v[70:71], off offset:64
	global_load_dwordx4 v[42:45], v[64:65], off offset:64
	global_load_dwordx4 v[34:37], v[68:69], off offset:128
	global_load_dwordx4 v[30:33], v[72:73], off offset:128
	global_load_dwordx4 v[26:29], v[70:71], off offset:128
	global_load_dwordx4 v[14:17], v[66:67], off offset:192
	global_load_dwordx4 v[18:21], v[68:69], off offset:192
	global_load_dwordx4 v[10:13], v[72:73], off offset:192
	global_load_dwordx4 v[6:9], v[70:71], off offset:192
	global_load_dwordx4 v[2:5], v[72:73], off offset:640
	global_load_dwordx4 v[104:107], v[64:65], off offset:128
	s_waitcnt vmcnt(17)
	ds_bpermute_b32 v54, v74, v54
	ds_bpermute_b32 v55, v74, v55
	ds_bpermute_b32 v56, v74, v56
	ds_bpermute_b32 v57, v74, v57
	s_waitcnt vmcnt(15)
	ds_bpermute_b32 v88, v74, v88
	ds_bpermute_b32 v89, v74, v89
	ds_bpermute_b32 v90, v74, v90
	ds_bpermute_b32 v91, v74, v91
	s_waitcnt vmcnt(13)
	ds_bpermute_b32 v96, v74, v96
	ds_bpermute_b32 v97, v74, v97
	ds_bpermute_b32 v98, v74, v98
	ds_bpermute_b32 v99, v74, v99
	ds_bpermute_b32 v39, v74, v39
	ds_bpermute_b32 v40, v74, v40
	ds_bpermute_b32 v41, v74, v41
	ds_bpermute_b32 v84, v74, v84
	ds_bpermute_b32 v85, v74, v85
	ds_bpermute_b32 v86, v74, v86
	ds_bpermute_b32 v87, v74, v87
	ds_bpermute_b32 v92, v74, v92
	ds_bpermute_b32 v93, v74, v93
	ds_bpermute_b32 v94, v74, v94
	ds_bpermute_b32 v95, v74, v95
	s_waitcnt lgkmcnt(8)
	v_mfma_f32_16x16x32_bf16 v[54:57], v[54:57], v[38:41], 0
	ds_bpermute_b32 v22, v74, v22
	ds_bpermute_b32 v23, v74, v23
	ds_bpermute_b32 v24, v74, v24
	v_mfma_f32_16x16x32_bf16 v[88:91], v[88:91], v[38:41], 0
	ds_bpermute_b32 v25, v74, v25
	s_and_b64 vcc, exec, s[6:7]
	s_waitcnt vmcnt(12)
	ds_bpermute_b32 v100, v74, v100
	ds_bpermute_b32 v101, v74, v101
	ds_bpermute_b32 v102, v74, v102
	ds_bpermute_b32 v103, v74, v103
	s_waitcnt vmcnt(9)
	ds_bpermute_b32 v42, v74, v42
	ds_bpermute_b32 v43, v74, v43
	ds_bpermute_b32 v44, v74, v44
	ds_bpermute_b32 v45, v74, v45
	v_mfma_f32_16x16x32_bf16 v[96:99], v[96:99], v[38:41], 0
	ds_bpermute_b32 v50, v74, v50
	ds_bpermute_b32 v51, v74, v51
	ds_bpermute_b32 v52, v74, v52
	s_waitcnt lgkmcnt(7)
	v_mfma_f32_16x16x32_bf16 v[38:41], v[100:103], v[38:41], 0
	ds_bpermute_b32 v53, v74, v53
	ds_bpermute_b32 v46, v74, v46
	ds_bpermute_b32 v47, v74, v47
	ds_bpermute_b32 v48, v74, v48
	ds_bpermute_b32 v49, v74, v49
	s_waitcnt vmcnt(8)
	ds_bpermute_b32 v34, v74, v34
	ds_bpermute_b32 v35, v74, v35
	ds_bpermute_b32 v36, v74, v36
	ds_bpermute_b32 v37, v74, v37
	s_waitcnt lgkmcnt(12)
	v_mfma_f32_16x16x32_bf16 v[38:41], v[42:45], v[84:87], v[38:41]
	global_load_dwordx4 v[42:45], v[64:65], off offset:192
	s_waitcnt vmcnt(8)
	ds_bpermute_b32 v30, v74, v30
	ds_bpermute_b32 v31, v74, v31
	v_mfma_f32_16x16x32_bf16 v[54:57], v[92:95], v[84:87], v[54:57]
	ds_bpermute_b32 v32, v74, v32
	ds_bpermute_b32 v33, v74, v33
	s_waitcnt vmcnt(7)
	ds_bpermute_b32 v26, v74, v26
	s_waitcnt lgkmcnt(13)
	v_mfma_f32_16x16x32_bf16 v[50:53], v[50:53], v[84:87], v[88:91]
	ds_bpermute_b32 v27, v74, v27
	ds_bpermute_b32 v28, v74, v28
	ds_bpermute_b32 v29, v74, v29
	s_waitcnt lgkmcnt(12)
	v_mfma_f32_16x16x32_bf16 v[46:49], v[46:49], v[84:87], v[96:99]
	s_waitcnt vmcnt(5)
	ds_bpermute_b32 v18, v74, v18
	ds_bpermute_b32 v19, v74, v19
	ds_bpermute_b32 v20, v74, v20
	s_waitcnt lgkmcnt(11)
	v_mfma_f32_16x16x32_bf16 v[34:37], v[34:37], v[22:25], v[54:57]
	s_nop 2
	global_load_dwordx4 v[54:57], v[66:67], off offset:256
	global_load_dwordx4 v[84:87], v[68:69], off offset:256
	global_load_dwordx4 v[88:91], v[70:71], off offset:256
	ds_bpermute_b32 v21, v74, v21
	s_waitcnt lgkmcnt(8)
	v_mfma_f32_16x16x32_bf16 v[30:33], v[30:33], v[22:25], v[50:53]
	ds_bpermute_b32 v14, v74, v14
	ds_bpermute_b32 v15, v74, v15
	ds_bpermute_b32 v16, v74, v16
	global_load_dwordx4 v[50:53], v[72:73], off offset:256
	s_waitcnt lgkmcnt(7)
	v_mfma_f32_16x16x32_bf16 v[26:29], v[26:29], v[22:25], v[46:49]
	ds_bpermute_b32 v17, v74, v17
	s_waitcnt vmcnt(8)
	ds_bpermute_b32 v10, v74, v10
	ds_bpermute_b32 v11, v74, v11
	s_waitcnt vmcnt(5)
	ds_bpermute_b32 v46, v74, v104
	ds_bpermute_b32 v47, v74, v105
	ds_bpermute_b32 v48, v74, v106
	ds_bpermute_b32 v49, v74, v107
	s_waitcnt lgkmcnt(0)
	v_mfma_f32_16x16x32_bf16 v[22:25], v[46:49], v[22:25], v[38:41]
	s_nop 2
	global_load_dwordx4 v[38:41], v[64:65], off offset:256
	ds_bpermute_b32 v12, v74, v12
	ds_bpermute_b32 v13, v74, v13
	v_mfma_f32_16x16x32_bf16 v[18:21], v[18:21], v[14:17], v[34:37]
	s_nop 2
	global_load_dwordx4 v[34:37], v[66:67], off offset:320
	global_load_dwordx4 v[46:49], v[68:69], off offset:320
	ds_bpermute_b32 v6, v74, v6
	ds_bpermute_b32 v7, v74, v7
	s_waitcnt lgkmcnt(2)
; #define SK_LOAD(b_, s0_) do { _Pragma("unroll") for (int u = 0; u < UB; ++u) if ((s0_) + u < STEPS) { af[b_][u] = *(const bf16x8*)(ap + ((s0_) + u) * 32); \
;                 _Pragma("unroll") for (int nt = 0; nt < 4; ++nt) wf[b_][u][nt] = *(const bf16x8*)(wp + (size_t)(16 * nt) * ldb + ((s0_) + u) * 32); } } while (0)
; #define SK_MMA(b_, s0_) do { _Pragma("unroll") for (int u = 0; u < UB; ++u) if ((s0_) + u < STEPS) { const bf16x8 afp = sk_perm(af[b_][u], pidx); \
;                 _Pragma("unroll") for (int nt = 0; nt < 4; ++nt) acc[p][nt] = __builtin_amdgcn_mfma_f32_16x16x32_bf16(sk_perm(wf[b_][u][nt], pidx), afp, acc[p][nt], 0, 0, 0); } } while (0)
; template <int NPARTS, int STEPS  , bool FINAL, class Epi> ...
;     ...
;             const bf16_t* wp = Bt + (size_t)(64 * cg + (lane >> 2)) * ldb + p * koff + w * (STEPS * 32) + 8 * (lane & 3);
;             const bf16_t* ap = A + (size_t)(MP + 16 * rg + (lane >> 2)) * lda + p * koff + w * (STEPS * 32) + 8 * (lane & 3);
;             constexpr int NB = (STEPS + UB - 1) / UB;
;             bf16x8 af[2][UB], wf[2][UB][4];
;     ...
;             SK_LOAD(0, 0);
; #pragma unroll
;             for (int b = 0; b < NB; ++b) {
;                 if (b + 1 < NB) { if ((b & 1) == 0) SK_LOAD(1, (b + 1) * UB); else SK_LOAD(0, (b + 1) * UB); }
;                 if ((b & 1) == 0) SK_MMA(0, b * UB); else SK_MMA(1, b * UB);
;             }
	v_mfma_f32_16x16x32_bf16 v[10:13], v[10:13], v[14:17], v[30:33]
	s_nop 2
	global_load_dwordx4 v[30:33], v[72:73], off offset:320
	ds_bpermute_b32 v8, v74, v8
	ds_bpermute_b32 v9, v74, v9
	s_waitcnt lgkmcnt(0)
	v_mfma_f32_16x16x32_bf16 v[6:9], v[6:9], v[14:17], v[26:29]
	ds_bpermute_b32 v2, v74, v2
	ds_bpermute_b32 v3, v74, v3
	ds_bpermute_b32 v4, v74, v4
	ds_bpermute_b32 v5, v74, v5
	s_waitcnt vmcnt(8)
	ds_bpermute_b32 v26, v74, v42
	ds_bpermute_b32 v27, v74, v43
	ds_bpermute_b32 v28, v74, v44
	ds_bpermute_b32 v29, v74, v45
	global_load_dwordx4 v[42:45], v[70:71], off offset:320
	s_waitcnt lgkmcnt(0)
	v_mfma_f32_16x16x32_bf16 v[14:17], v[26:29], v[14:17], v[22:25]
	s_waitcnt vmcnt(8)
	ds_bpermute_b32 v26, v74, v54
	s_waitcnt vmcnt(7)
	ds_bpermute_b32 v22, v74, v84
	ds_bpermute_b32 v23, v74, v85
	ds_bpermute_b32 v24, v74, v86
	ds_bpermute_b32 v25, v74, v87
	ds_bpermute_b32 v27, v74, v55
	ds_bpermute_b32 v28, v74, v56
	ds_bpermute_b32 v29, v74, v57
	global_load_dwordx4 v[54:57], v[64:65], off offset:320
	s_waitcnt lgkmcnt(0)
	v_mfma_f32_16x16x32_bf16 v[18:21], v[22:25], v[26:29], v[18:21]
	s_waitcnt vmcnt(6)
	ds_bpermute_b32 v22, v74, v50
	ds_bpermute_b32 v23, v74, v51
	ds_bpermute_b32 v24, v74, v52
	ds_bpermute_b32 v25, v74, v53
	global_load_dwordx4 v[50:53], v[66:67], off offset:384
	global_load_dwordx4 v[84:87], v[68:69], off offset:384
	s_waitcnt lgkmcnt(0)
	v_mfma_f32_16x16x32_bf16 v[10:13], v[22:25], v[26:29], v[10:13]
	ds_bpermute_b32 v22, v74, v88
	ds_bpermute_b32 v23, v74, v89
	ds_bpermute_b32 v24, v74, v90
	ds_bpermute_b32 v25, v74, v91
	global_load_dwordx4 v[88:91], v[72:73], off offset:384
	s_waitcnt lgkmcnt(0)
	v_mfma_f32_16x16x32_bf16 v[6:9], v[22:25], v[26:29], v[6:9]
	s_waitcnt vmcnt(8)
	ds_bpermute_b32 v22, v74, v38
	ds_bpermute_b32 v23, v74, v39
	ds_bpermute_b32 v24, v74, v40
	ds_bpermute_b32 v25, v74, v41
	global_load_dwordx4 v[38:41], v[70:71], off offset:384
	s_waitcnt lgkmcnt(0)
	v_mfma_f32_16x16x32_bf16 v[14:17], v[22:25], v[26:29], v[14:17]
	s_waitcnt vmcnt(8)
	ds_bpermute_b32 v26, v74, v34
	ds_bpermute_b32 v27, v74, v35
	ds_bpermute_b32 v28, v74, v36
	ds_bpermute_b32 v29, v74, v37
	global_load_dwordx4 v[34:37], v[64:65], off offset:384
	s_waitcnt vmcnt(8)
	ds_bpermute_b32 v22, v74, v46
	ds_bpermute_b32 v23, v74, v47
	ds_bpermute_b32 v24, v74, v48
	ds_bpermute_b32 v25, v74, v49
	s_waitcnt lgkmcnt(0)
	v_mfma_f32_16x16x32_bf16 v[18:21], v[22:25], v[26:29], v[18:21]
	s_waitcnt vmcnt(7)
	ds_bpermute_b32 v22, v74, v30
	ds_bpermute_b32 v23, v74, v31
	ds_bpermute_b32 v24, v74, v32
	ds_bpermute_b32 v25, v74, v33
	global_load_dwordx4 v[30:33], v[66:67], off offset:448
	global_load_dwordx4 v[46:49], v[68:69], off offset:448
	s_waitcnt lgkmcnt(0)
	v_mfma_f32_16x16x32_bf16 v[10:13], v[22:25], v[26:29], v[10:13]
	s_waitcnt vmcnt(8)
	ds_bpermute_b32 v22, v74, v42
	ds_bpermute_b32 v23, v74, v43
	ds_bpermute_b32 v24, v74, v44
	ds_bpermute_b32 v25, v74, v45
	global_load_dwordx4 v[42:45], v[72:73], off offset:448
	s_waitcnt lgkmcnt(0)
	v_mfma_f32_16x16x32_bf16 v[6:9], v[22:25], v[26:29], v[6:9]
	s_waitcnt vmcnt(8)
	ds_bpermute_b32 v22, v74, v54
	ds_bpermute_b32 v23, v74, v55
	ds_bpermute_b32 v24, v74, v56
	ds_bpermute_b32 v25, v74, v57
	global_load_dwordx4 v[54:57], v[70:71], off offset:448
	s_waitcnt lgkmcnt(0)
	v_mfma_f32_16x16x32_bf16 v[14:17], v[22:25], v[26:29], v[14:17]
	s_waitcnt vmcnt(7)
	ds_bpermute_b32 v22, v74, v84
	ds_bpermute_b32 v23, v74, v85
	ds_bpermute_b32 v24, v74, v86
	ds_bpermute_b32 v25, v74, v87
	ds_bpermute_b32 v26, v74, v50
	ds_bpermute_b32 v27, v74, v51
	ds_bpermute_b32 v28, v74, v52
	ds_bpermute_b32 v29, v74, v53
	global_load_dwordx4 v[50:53], v[64:65], off offset:448
	s_waitcnt lgkmcnt(0)
	v_mfma_f32_16x16x32_bf16 v[18:21], v[22:25], v[26:29], v[18:21]
	s_waitcnt vmcnt(7)
	ds_bpermute_b32 v22, v74, v88
	ds_bpermute_b32 v23, v74, v89
	ds_bpermute_b32 v24, v74, v90
	ds_bpermute_b32 v25, v74, v91
	global_load_dwordx4 v[84:87], v[66:67], off offset:512
	global_load_dwordx4 v[88:91], v[68:69], off offset:512
	s_waitcnt lgkmcnt(0)
	v_mfma_f32_16x16x32_bf16 v[10:13], v[22:25], v[26:29], v[10:13]
	s_waitcnt vmcnt(8)
	ds_bpermute_b32 v22, v74, v38
	ds_bpermute_b32 v23, v74, v39
	ds_bpermute_b32 v24, v74, v40
	ds_bpermute_b32 v25, v74, v41
	global_load_dwordx4 v[38:41], v[72:73], off offset:512
	s_waitcnt lgkmcnt(0)
	v_mfma_f32_16x16x32_bf16 v[6:9], v[22:25], v[26:29], v[6:9]
	s_waitcnt vmcnt(8)
	ds_bpermute_b32 v22, v74, v34
	ds_bpermute_b32 v23, v74, v35
	ds_bpermute_b32 v24, v74, v36
	ds_bpermute_b32 v25, v74, v37
	global_load_dwordx4 v[34:37], v[70:71], off offset:512
	s_waitcnt lgkmcnt(0)
	v_mfma_f32_16x16x32_bf16 v[14:17], v[22:25], v[26:29], v[14:17]
	s_waitcnt vmcnt(8)
	ds_bpermute_b32 v26, v74, v30
	ds_bpermute_b32 v27, v74, v31
	ds_bpermute_b32 v28, v74, v32
	ds_bpermute_b32 v29, v74, v33
	global_load_dwordx4 v[30:33], v[64:65], off offset:512
	s_waitcnt vmcnt(8)
	ds_bpermute_b32 v22, v74, v46
	ds_bpermute_b32 v23, v74, v47
	ds_bpermute_b32 v24, v74, v48
	ds_bpermute_b32 v25, v74, v49
	s_waitcnt lgkmcnt(0)
	v_mfma_f32_16x16x32_bf16 v[18:21], v[22:25], v[26:29], v[18:21]
	s_waitcnt vmcnt(7)
	ds_bpermute_b32 v22, v74, v42
	ds_bpermute_b32 v23, v74, v43
	ds_bpermute_b32 v24, v74, v44
	ds_bpermute_b32 v25, v74, v45
	s_waitcnt lgkmcnt(0)
	v_mfma_f32_16x16x32_bf16 v[10:13], v[22:25], v[26:29], v[10:13]
	s_waitcnt vmcnt(6)
	ds_bpermute_b32 v22, v74, v54
	ds_bpermute_b32 v23, v74, v55
	ds_bpermute_b32 v24, v74, v56
	ds_bpermute_b32 v25, v74, v57
	global_load_dwordx4 v[42:45], v[66:67], off offset:576
	global_load_dwordx4 v[46:49], v[68:69], off offset:576
	s_waitcnt lgkmcnt(0)
; #define SK_LOAD(b_, s0_) do { _Pragma("unroll") for (int u = 0; u < UB; ++u) if ((s0_) + u < STEPS) { af[b_][u] = *(const bf16x8*)(ap + ((s0_) + u) * 32); \
;                 _Pragma("unroll") for (int nt = 0; nt < 4; ++nt) wf[b_][u][nt] = *(const bf16x8*)(wp + (size_t)(16 * nt) * ldb + ((s0_) + u) * 32); } } while (0)
; #define SK_MMA(b_, s0_) do { _Pragma("unroll") for (int u = 0; u < UB; ++u) if ((s0_) + u < STEPS) { const bf16x8 afp = sk_perm(af[b_][u], pidx); \
;                 _Pragma("unroll") for (int nt = 0; nt < 4; ++nt) acc[p][nt] = __builtin_amdgcn_mfma_f32_16x16x32_bf16(sk_perm(wf[b_][u][nt], pidx), afp, acc[p][nt], 0, 0, 0); } } while (0)
; template <int NPARTS, int STEPS  , bool FINAL, class Epi> ...
;     ...
;             SK_LOAD(0, 0);
; #pragma unroll
;             for (int b = 0; b < NB; ++b) {
;                 if (b + 1 < NB) { if ((b & 1) == 0) SK_LOAD(1, (b + 1) * UB); else SK_LOAD(0, (b + 1) * UB); }
;                 if ((b & 1) == 0) SK_MMA(0, b * UB); else SK_MMA(1, b * UB);
;             }
;     ...
;         }
; #pragma unroll
;         for (int p = 0; p < NPARTS; ++p)
; #pragma unroll
;             for (int nt = 0; nt < 4; ++nt) red[((w * NPARTS + p) * 4 + nt) * 64 + lane] = acc[p][nt];
;         __syncthreads();
;         f32x4 o = (f32x4){0.f, 0.f, 0.f, 0.f};
;         if (w < 4) {
;             f32x4 a2[NPARTS];
; #pragma unroll
;             for (int p = 0; p < NPARTS; ++p) { a2[p] = (f32x4){0.f, 0.f, 0.f, 0.f};
; #pragma unroll
;                 for (int w2 = 0; w2 < 8; ++w2) a2[p] += red[((w2 * NPARTS + p) * 4 + w) * 64 + lane]; }
;             const int row = MP + 16 * rg + fr, c0 = 64 * cg + 16 * w + 4 * fq;
;             o = E(row, c0, a2);
;             float s = (o[0] * o[0] + o[1] * o[1]) + (o[2] * o[2] + o[3] * o[3]);
;             s += __shfl_xor(s, 16); s += __shfl_xor(s, 32);
;             if (fq == 0) sred[w * 16 + fr] = s;
;     __device__ __forceinline__ f32x4 operator()(int row, int c0, const f32x4 (&acc)[1]) const {
;         const size_t off = (size_t)row * D + c0;
;         f32x4 b;
;         if (BASE_BF16) b = unpack4(*(const u32x2*)((const bf16_t*)base + off)); else b = *(const f32x4*)((const float*)base + (off - (size_t)MP * D));
;         const f32x4 v = b + acc[0] * scale;
;         if (OUT_F32) *(f32x4*)(outf + off) = v;
;         if (OUT_BF16) *(u32x2*)(outb + off) = pack4(v);
;         return v;
	v_mfma_f32_16x16x32_bf16 v[6:9], v[22:25], v[26:29], v[6:9]
	s_waitcnt vmcnt(7)
	ds_bpermute_b32 v22, v74, v50
	ds_bpermute_b32 v23, v74, v51
	ds_bpermute_b32 v24, v74, v52
	ds_bpermute_b32 v25, v74, v53
	global_load_dwordx4 v[54:57], v[72:73], off offset:576
	s_waitcnt lgkmcnt(0)
	v_mfma_f32_16x16x32_bf16 v[14:17], v[22:25], v[26:29], v[14:17]
	s_waitcnt vmcnt(6)
	ds_bpermute_b32 v22, v74, v88
	ds_bpermute_b32 v23, v74, v89
	ds_bpermute_b32 v24, v74, v90
	ds_bpermute_b32 v25, v74, v91
	global_load_dwordx4 v[50:53], v[70:71], off offset:576
	ds_bpermute_b32 v26, v74, v84
	ds_bpermute_b32 v27, v74, v85
	ds_bpermute_b32 v28, v74, v86
	ds_bpermute_b32 v29, v74, v87
	s_waitcnt lgkmcnt(0)
	v_mfma_f32_16x16x32_bf16 v[18:21], v[22:25], v[26:29], v[18:21]
	s_waitcnt vmcnt(6)
	ds_bpermute_b32 v22, v74, v38
	ds_bpermute_b32 v23, v74, v39
	ds_bpermute_b32 v24, v74, v40
	ds_bpermute_b32 v25, v74, v41
	global_load_dwordx4 v[84:87], v[64:65], off offset:576
	s_waitcnt lgkmcnt(0)
	v_mfma_f32_16x16x32_bf16 v[10:13], v[22:25], v[26:29], v[10:13]
	s_waitcnt vmcnt(6)
	ds_bpermute_b32 v22, v74, v34
	ds_bpermute_b32 v23, v74, v35
	ds_bpermute_b32 v24, v74, v36
	ds_bpermute_b32 v25, v74, v37
	global_load_dwordx4 v[38:41], v[66:67], off offset:640
	s_nop 0
	global_load_dwordx4 v[66:69], v[68:69], off offset:640
	s_waitcnt lgkmcnt(0)
	v_mfma_f32_16x16x32_bf16 v[6:9], v[22:25], v[26:29], v[6:9]
	s_waitcnt vmcnt(7)
	ds_bpermute_b32 v22, v74, v30
	ds_bpermute_b32 v23, v74, v31
	ds_bpermute_b32 v24, v74, v32
	ds_bpermute_b32 v25, v74, v33
	global_load_dwordx4 v[30:33], v[70:71], off offset:640
	global_load_dwordx4 v[34:37], v[64:65], off offset:640
	s_waitcnt lgkmcnt(0)
	v_mfma_f32_16x16x32_bf16 v[14:17], v[22:25], v[26:29], v[14:17]
	s_waitcnt vmcnt(8)
	ds_bpermute_b32 v26, v74, v42
	s_waitcnt vmcnt(7)
	ds_bpermute_b32 v22, v74, v46
	ds_bpermute_b32 v23, v74, v47
	ds_bpermute_b32 v24, v74, v48
	ds_bpermute_b32 v25, v74, v49
	ds_bpermute_b32 v27, v74, v43
	ds_bpermute_b32 v28, v74, v44
	ds_bpermute_b32 v29, v74, v45
	s_waitcnt lgkmcnt(0)
	v_mfma_f32_16x16x32_bf16 v[18:21], v[22:25], v[26:29], v[18:21]
	s_waitcnt vmcnt(6)
	ds_bpermute_b32 v22, v74, v54
	ds_bpermute_b32 v23, v74, v55
	ds_bpermute_b32 v24, v74, v56
	ds_bpermute_b32 v25, v74, v57
	s_waitcnt lgkmcnt(0)
	v_mfma_f32_16x16x32_bf16 v[10:13], v[22:25], v[26:29], v[10:13]
	s_waitcnt vmcnt(5)
	ds_bpermute_b32 v22, v74, v50
	ds_bpermute_b32 v23, v74, v51
	ds_bpermute_b32 v24, v74, v52
	ds_bpermute_b32 v25, v74, v53
	s_waitcnt lgkmcnt(0)
	v_mfma_f32_16x16x32_bf16 v[6:9], v[22:25], v[26:29], v[6:9]
	s_waitcnt vmcnt(4)
	ds_bpermute_b32 v22, v74, v84
	ds_bpermute_b32 v23, v74, v85
	ds_bpermute_b32 v24, v74, v86
	ds_bpermute_b32 v25, v74, v87
	s_waitcnt lgkmcnt(0)
	v_mfma_f32_16x16x32_bf16 v[14:17], v[22:25], v[26:29], v[14:17]
	s_waitcnt vmcnt(3)
	ds_bpermute_b32 v26, v74, v38
	ds_bpermute_b32 v27, v74, v39
	ds_bpermute_b32 v28, v74, v40
	ds_bpermute_b32 v29, v74, v41
	s_waitcnt lgkmcnt(0)
	v_mfma_f32_16x16x32_bf16 v[2:5], v[2:5], v[26:29], v[10:13]
	s_waitcnt vmcnt(2)
	ds_bpermute_b32 v22, v74, v66
	ds_bpermute_b32 v23, v74, v67
	ds_bpermute_b32 v24, v74, v68
	ds_bpermute_b32 v25, v74, v69
	s_waitcnt vmcnt(1)
	ds_bpermute_b32 v10, v74, v30
	ds_bpermute_b32 v11, v74, v31
	ds_bpermute_b32 v12, v74, v32
	ds_bpermute_b32 v13, v74, v33
	s_waitcnt lgkmcnt(0)
	v_mfma_f32_16x16x32_bf16 v[6:9], v[10:13], v[26:29], v[6:9]
	s_waitcnt vmcnt(0)
	ds_bpermute_b32 v10, v74, v34
	ds_bpermute_b32 v11, v74, v35
	ds_bpermute_b32 v12, v74, v36
	ds_bpermute_b32 v13, v74, v37
	v_mfma_f32_16x16x32_bf16 v[18:21], v[22:25], v[26:29], v[18:21]
	s_waitcnt lgkmcnt(0)
	v_mfma_f32_16x16x32_bf16 v[10:13], v[10:13], v[26:29], v[14:17]
	s_nop 5
	ds_write_b128 v82, v[18:21]
	ds_write_b128 v82, v[2:5] offset:1024
	ds_write_b128 v82, v[6:9] offset:2048
	ds_write_b128 v82, v[10:13] offset:3072
	s_waitcnt lgkmcnt(0)
	s_barrier
	s_cbranch_vccnz .LBB0_708
	v_add_u32_e32 v2, s21, v75
	v_ashrrev_i32_e32 v3, 31, v2
	v_or_b32_e32 v4, s18, v81
	v_lshlrev_b64 v[2:3], 11, v[2:3]
	v_lshl_add_u64 v[2:3], s[88:89], 0, v[2:3]
	v_lshlrev_b32_e32 v58, 1, v4
	v_lshl_add_u64 v[34:35], v[2:3], 0, v[58:59]
	global_load_dwordx2 v[36:37], v[34:35], off
	ds_read_b128 v[2:5], v79
	ds_read_b128 v[6:9], v79 offset:4096
	ds_read_b128 v[10:13], v79 offset:8192
	ds_read_b128 v[14:17], v79 offset:12288
	ds_read_b128 v[18:21], v79 offset:16384
	ds_read_b128 v[22:25], v79 offset:20480
	ds_read_b128 v[26:29], v79 offset:24576
	ds_read_b128 v[30:33], v79 offset:28672
	s_waitcnt lgkmcnt(7)
	v_pk_add_f32 v[4:5], v[4:5], 0 op_sel_hi:[1,0]
	v_pk_add_f32 v[2:3], v[2:3], 0 op_sel_hi:[1,0]
	s_waitcnt lgkmcnt(6)
	v_pk_add_f32 v[4:5], v[4:5], v[8:9]
	v_pk_add_f32 v[2:3], v[2:3], v[6:7]
	s_waitcnt lgkmcnt(5)
	v_pk_add_f32 v[4:5], v[4:5], v[12:13]
	v_pk_add_f32 v[2:3], v[2:3], v[10:11]
	s_waitcnt lgkmcnt(4)
	v_pk_add_f32 v[4:5], v[4:5], v[16:17]
	v_pk_add_f32 v[2:3], v[2:3], v[14:15]
	s_waitcnt lgkmcnt(3)
	v_pk_add_f32 v[4:5], v[4:5], v[20:21]
	v_pk_add_f32 v[2:3], v[2:3], v[18:19]
	s_waitcnt lgkmcnt(2)
	v_pk_add_f32 v[4:5], v[4:5], v[24:25]
	v_pk_add_f32 v[2:3], v[2:3], v[22:23]
	s_waitcnt lgkmcnt(1)
	v_pk_add_f32 v[4:5], v[4:5], v[28:29]
	v_pk_add_f32 v[2:3], v[2:3], v[26:27]
	v_and_b32_e32 v39, 64, v83
	s_waitcnt lgkmcnt(0)
	v_pk_add_f32 v[4:5], v[4:5], v[32:33]
	v_pk_add_f32 v[2:3], v[2:3], v[30:31]
	v_xor_b32_e32 v38, 16, v83
	v_add_u32_e32 v39, 64, v39
	v_cmp_lt_i32_e32 vcc, v38, v39
	s_waitcnt vmcnt(0)
	v_lshlrev_b32_e32 v6, 16, v36
	v_and_b32_e32 v7, 0xffff0000, v36
	v_lshlrev_b32_e32 v8, 16, v37
	v_and_b32_e32 v9, 0xffff0000, v37
	v_pk_fma_f32 v[4:5], v[4:5], 0.5, v[8:9] op_sel_hi:[1,0,1]
	v_pk_fma_f32 v[6:7], v[2:3], 0.5, v[6:7] op_sel_hi:[1,0,1]
	v_mul_f32_e32 v3, v5, v5
	v_mul_f32_e32 v2, v7, v7
	v_cndmask_b32_e32 v38, v83, v38, vcc
	v_fmac_f32_e32 v2, v6, v6
	v_fmac_f32_e32 v3, v4, v4
	v_lshlrev_b32_e32 v38, 2, v38
	v_add_f32_e32 v2, v2, v3
	v_mov_b32_e32 v3, v2
	s_nop 1
	v_permlane16_swap_b32_e32 v2, v3
	v_xor_b32_e32 v8, 32, v83
	v_cmp_lt_i32_e32 vcc, v8, v39
	v_cvt_pk_bf16_f32 v6, v6, v7
	v_cvt_pk_bf16_f32 v7, v4, v5
	v_cndmask_b32_e32 v8, v83, v8, vcc
	s_waitcnt lgkmcnt(0)
	v_add_f32_e32 v2, v2, v3
	v_lshlrev_b32_e32 v3, 2, v8
	v_mov_b32_e32 v3, v2
	s_nop 1
	v_permlane32_swap_b32_e32 v2, v3
	global_store_dwordx2 v[34:35], v[6:7], off
	s_and_saveexec_b64 s[18:19], s[0:1]
	s_cbranch_execz .LBB0_707
	s_waitcnt lgkmcnt(0)
	v_add_f32_e32 v2, v2, v3
	ds_write_b32 v80, v2 offset:32768

; #define SK_LOAD(b_, s0_) do { _Pragma("unroll") for (int u = 0; u < UB; ++u) if ((s0_) + u < STEPS) { af[b_][u] = *(const bf16x8*)(ap + ((s0_) + u) * 32); \
;                 _Pragma("unroll") for (int nt = 0; nt < 4; ++nt) wf[b_][u][nt] = *(const bf16x8*)(wp + (size_t)(16 * nt) * ldb + ((s0_) + u) * 32); } } while (0)
; #define SK_MMA(b_, s0_) do { _Pragma("unroll") for (int u = 0; u < UB; ++u) if ((s0_) + u < STEPS) { const bf16x8 afp = sk_perm(af[b_][u], pidx); \
;                 _Pragma("unroll") for (int nt = 0; nt < 4; ++nt) acc[p][nt] = __builtin_amdgcn_mfma_f32_16x16x32_bf16(sk_perm(wf[b_][u][nt], pidx), afp, acc[p][nt], 0, 0, 0); } } while (0)
; template <int NPARTS, int STEPS  , bool FINAL, class Epi> ...
;     ...
;         for (int p = 0; p < NPARTS; ++p) {
; #pragma unroll
;             for (int nt = 0; nt < 4; ++nt) acc[p][nt] = (f32x4){0.f, 0.f, 0.f, 0.f};
;             const bf16_t* wp = Bt + (size_t)(64 * cg + (lane >> 2)) * ldb + p * koff + w * (STEPS * 32) + 8 * (lane & 3);
;             const bf16_t* ap = A + (size_t)(MP + 16 * rg + (lane >> 2)) * lda + p * koff + w * (STEPS * 32) + 8 * (lane & 3);
;             constexpr int NB = (STEPS + UB - 1) / UB;
;             bf16x8 af[2][UB], wf[2][UB][4];
;     ...
;             SK_LOAD(0, 0);
; #pragma unroll
;             for (int b = 0; b < NB; ++b) {
;                 if (b + 1 < NB) { if ((b & 1) == 0) SK_LOAD(1, (b + 1) * UB); else SK_LOAD(0, (b + 1) * UB); }
;                 if ((b & 1) == 0) SK_MMA(0, b * UB); else SK_MMA(1, b * UB);
;             }
.LBB0_1390:
	global_load_dwordx4 v[84:87], v[24:25], off
	global_load_dwordx4 v[88:91], v[26:27], off
	global_load_dwordx4 v[92:95], v[28:29], off
	global_load_dwordx4 v[96:99], v[30:31], off
	global_load_dwordx4 v[100:103], v[24:25], off offset:64
	global_load_dwordx4 v[104:107], v[32:33], off
	s_and_b32 s10, s13, -16
	v_add_u32_e32 v2, s10, v80
	v_ashrrev_i32_e32 v3, 31, v2
	v_lshlrev_b64 v[2:3], 12, v[2:3]
	v_lshl_add_u64 v[76:77], v[22:23], 0, v[2:3]
	global_load_dwordx4 v[108:111], v[76:77], off
	global_load_dwordx4 v[112:115], v[34:35], off
	global_load_dwordx4 v[116:119], v[36:37], off
	global_load_dwordx4 v[120:123], v[76:77], off offset:64
	global_load_dwordx4 v[124:127], v[24:25], off offset:128
	global_load_dwordx4 v[128:131], v[38:39], off
	global_load_dwordx4 v[132:135], v[76:77], off offset:128
	global_load_dwordx4 v[136:139], v[40:41], off
	global_load_dwordx4 v[18:21], v[42:43], off
	global_load_dwordx4 v[14:17], v[24:25], off offset:192
	global_load_dwordx4 v[10:13], v[44:45], off
	global_load_dwordx4 v[6:9], v[46:47], off
	global_load_dwordx4 v[2:5], v[48:49], off
	global_load_dwordx4 v[140:143], v[24:25], off offset:2048
	global_load_dwordx4 v[144:147], v[76:77], off offset:192
	global_load_dwordx4 v[148:151], v[76:77], off offset:2048
	s_andn2_b64 vcc, exec, s[6:7]
	s_waitcnt vmcnt(15)
	ds_bpermute_b32 v108, v78, v108
	ds_bpermute_b32 v109, v78, v109
	ds_bpermute_b32 v110, v78, v110
	ds_bpermute_b32 v111, v78, v111
	ds_bpermute_b32 v84, v78, v84
	ds_bpermute_b32 v85, v78, v85
	ds_bpermute_b32 v86, v78, v86
	ds_bpermute_b32 v87, v78, v87
	ds_bpermute_b32 v88, v78, v88
	ds_bpermute_b32 v89, v78, v89
	ds_bpermute_b32 v90, v78, v90
	ds_bpermute_b32 v91, v78, v91
	ds_bpermute_b32 v100, v78, v100
	ds_bpermute_b32 v101, v78, v101
	ds_bpermute_b32 v102, v78, v102
	ds_bpermute_b32 v103, v78, v103
	ds_bpermute_b32 v92, v78, v92
	ds_bpermute_b32 v93, v78, v93
	ds_bpermute_b32 v94, v78, v94
	ds_bpermute_b32 v95, v78, v95
	ds_bpermute_b32 v96, v78, v96
	ds_bpermute_b32 v97, v78, v97
	ds_bpermute_b32 v98, v78, v98
	ds_bpermute_b32 v99, v78, v99
	ds_bpermute_b32 v104, v78, v104
	ds_bpermute_b32 v105, v78, v105
	ds_bpermute_b32 v106, v78, v106
	ds_bpermute_b32 v107, v78, v107
	s_waitcnt vmcnt(12)
	ds_bpermute_b32 v120, v78, v120
	ds_bpermute_b32 v121, v78, v121
	ds_bpermute_b32 v122, v78, v122
	ds_bpermute_b32 v123, v78, v123
	s_waitcnt lgkmcnt(14)
	v_mfma_f32_16x16x32_bf16 v[84:87], v[84:87], v[108:111], 0
	ds_bpermute_b32 v116, v78, v116
	ds_bpermute_b32 v117, v78, v117
	ds_bpermute_b32 v118, v78, v118
	v_mfma_f32_16x16x32_bf16 v[88:91], v[88:91], v[108:111], 0
	ds_bpermute_b32 v119, v78, v119
	ds_bpermute_b32 v112, v78, v112
	ds_bpermute_b32 v113, v78, v113
	s_waitcnt lgkmcnt(6)
	v_mfma_f32_16x16x32_bf16 v[84:87], v[100:103], v[120:123], v[84:87]
	s_waitcnt vmcnt(10)
	ds_bpermute_b32 v100, v78, v128
	ds_bpermute_b32 v101, v78, v129
	ds_bpermute_b32 v102, v78, v130
	ds_bpermute_b32 v103, v78, v131
	v_mfma_f32_16x16x32_bf16 v[92:95], v[92:95], v[108:111], 0
	ds_bpermute_b32 v114, v78, v114
	ds_bpermute_b32 v115, v78, v115
	s_waitcnt vmcnt(7)
	ds_bpermute_b32 v18, v78, v18
	v_mfma_f32_16x16x32_bf16 v[96:99], v[96:99], v[108:111], 0
	ds_bpermute_b32 v108, v78, v124
	ds_bpermute_b32 v109, v78, v125
	ds_bpermute_b32 v110, v78, v126
	ds_bpermute_b32 v111, v78, v127
	v_mfma_f32_16x16x32_bf16 v[88:91], v[104:107], v[120:123], v[88:91]
	ds_bpermute_b32 v104, v78, v132
	ds_bpermute_b32 v105, v78, v133
	ds_bpermute_b32 v106, v78, v134
	ds_bpermute_b32 v107, v78, v135
	ds_bpermute_b32 v19, v78, v19
	ds_bpermute_b32 v20, v78, v20
	ds_bpermute_b32 v21, v78, v21
	s_waitcnt vmcnt(6)
	ds_bpermute_b32 v14, v78, v14
	ds_bpermute_b32 v15, v78, v15
	ds_bpermute_b32 v16, v78, v16
	ds_bpermute_b32 v17, v78, v17
	s_waitcnt lgkmcnt(7)
	v_mfma_f32_16x16x32_bf16 v[88:91], v[100:103], v[104:107], v[88:91]
	s_waitcnt vmcnt(1)
	ds_bpermute_b32 v100, v78, v144
	ds_bpermute_b32 v101, v78, v145
	ds_bpermute_b32 v102, v78, v146
	ds_bpermute_b32 v103, v78, v147
	v_mfma_f32_16x16x32_bf16 v[96:99], v[116:119], v[120:123], v[96:99]
	ds_bpermute_b32 v10, v78, v10
	ds_bpermute_b32 v11, v78, v11
	ds_bpermute_b32 v12, v78, v12
	v_mfma_f32_16x16x32_bf16 v[84:87], v[108:111], v[104:107], v[84:87]
	global_load_dwordx4 v[108:111], v[50:51], off
	ds_bpermute_b32 v13, v78, v13
	ds_bpermute_b32 v6, v78, v6
	v_mfma_f32_16x16x32_bf16 v[92:95], v[112:115], v[120:123], v[92:95]
	ds_bpermute_b32 v112, v78, v136
	ds_bpermute_b32 v113, v78, v137
	ds_bpermute_b32 v114, v78, v138
	ds_bpermute_b32 v115, v78, v139
	s_waitcnt lgkmcnt(14)
	v_mfma_f32_16x16x32_bf16 v[18:21], v[18:21], v[104:107], v[96:99]
	ds_bpermute_b32 v7, v78, v7
	ds_bpermute_b32 v8, v78, v8
	ds_bpermute_b32 v9, v78, v9
	global_load_dwordx4 v[96:99], v[52:53], off
	s_waitcnt lgkmcnt(12)
	v_mfma_f32_16x16x32_bf16 v[14:17], v[14:17], v[100:103], v[84:87]
	global_load_dwordx4 v[116:119], v[60:61], off
	ds_bpermute_b32 v2, v78, v2
	ds_bpermute_b32 v3, v78, v3
	global_load_dwordx4 v[84:87], v[54:55], off
	s_waitcnt lgkmcnt(5)
	v_mfma_f32_16x16x32_bf16 v[92:95], v[112:115], v[104:107], v[92:95]
	global_load_dwordx4 v[104:107], v[76:77], off offset:2112
	global_load_dwordx4 v[112:115], v[56:57], off
	ds_bpermute_b32 v4, v78, v4
	v_mfma_f32_16x16x32_bf16 v[10:13], v[10:13], v[100:103], v[88:91]
	ds_bpermute_b32 v5, v78, v5
	s_waitcnt vmcnt(4)
	ds_bpermute_b32 v96, v78, v96
	global_load_dwordx4 v[88:91], v[24:25], off offset:2112
	s_waitcnt lgkmcnt(5)
; #define SK_LOAD(b_, s0_) do { _Pragma("unroll") for (int u = 0; u < UB; ++u) if ((s0_) + u < STEPS) { af[b_][u] = *(const bf16x8*)(ap + ((s0_) + u) * 32); \
;                 _Pragma("unroll") for (int nt = 0; nt < 4; ++nt) wf[b_][u][nt] = *(const bf16x8*)(wp + (size_t)(16 * nt) * ldb + ((s0_) + u) * 32); } } while (0)
; #define SK_MMA(b_, s0_) do { _Pragma("unroll") for (int u = 0; u < UB; ++u) if ((s0_) + u < STEPS) { const bf16x8 afp = sk_perm(af[b_][u], pidx); \
;                 _Pragma("unroll") for (int nt = 0; nt < 4; ++nt) acc[p][nt] = __builtin_amdgcn_mfma_f32_16x16x32_bf16(sk_perm(wf[b_][u][nt], pidx), afp, acc[p][nt], 0, 0, 0); } } while (0)
; template <int NPARTS, int STEPS  , bool FINAL, class Epi> ...
;     ...
;             SK_LOAD(0, 0);
; #pragma unroll
;             for (int b = 0; b < NB; ++b) {
;                 if (b + 1 < NB) { if ((b & 1) == 0) SK_LOAD(1, (b + 1) * UB); else SK_LOAD(0, (b + 1) * UB); }
;                 if ((b & 1) == 0) SK_MMA(0, b * UB); else SK_MMA(1, b * UB);
;             }
;     ...
;         }
; #pragma unroll
;         for (int p = 0; p < NPARTS; ++p)
; #pragma unroll
;             for (int nt = 0; nt < 4; ++nt) red[((w * NPARTS + p) * 4 + nt) * 64 + lane] = acc[p][nt];
;         __syncthreads();
	v_mfma_f32_16x16x32_bf16 v[6:9], v[6:9], v[100:103], v[92:95]
	ds_bpermute_b32 v108, v78, v108
	ds_bpermute_b32 v109, v78, v109
	ds_bpermute_b32 v110, v78, v110
	global_load_dwordx4 v[92:95], v[58:59], off
	global_load_dwordx4 v[120:123], v[76:77], off offset:2176
	global_load_dwordx4 v[124:127], v[24:25], off offset:2176
	global_load_dwordx4 v[128:131], v[62:63], off
	global_load_dwordx4 v[132:135], v[64:65], off
	s_waitcnt lgkmcnt(4)
	v_mfma_f32_16x16x32_bf16 v[2:5], v[2:5], v[100:103], v[18:21]
	ds_bpermute_b32 v111, v78, v111
	ds_bpermute_b32 v97, v78, v97
	ds_bpermute_b32 v98, v78, v98
	ds_bpermute_b32 v18, v78, v140
	ds_bpermute_b32 v19, v78, v141
	ds_bpermute_b32 v20, v78, v142
	ds_bpermute_b32 v21, v78, v143
	ds_bpermute_b32 v99, v78, v99
	s_waitcnt vmcnt(8)
	ds_bpermute_b32 v84, v78, v84
	ds_bpermute_b32 v85, v78, v85
	ds_bpermute_b32 v86, v78, v86
	ds_bpermute_b32 v87, v78, v87
	ds_bpermute_b32 v100, v78, v148
	ds_bpermute_b32 v101, v78, v149
	ds_bpermute_b32 v102, v78, v150
	ds_bpermute_b32 v103, v78, v151
	s_waitcnt lgkmcnt(0)
	v_mfma_f32_16x16x32_bf16 v[18:21], v[18:21], v[100:103], 0
	s_waitcnt vmcnt(5)
	ds_bpermute_b32 v88, v78, v88
	v_mfma_f32_16x16x32_bf16 v[108:111], v[108:111], v[100:103], 0
	ds_bpermute_b32 v89, v78, v89
	ds_bpermute_b32 v90, v78, v90
	ds_bpermute_b32 v91, v78, v91
	v_mfma_f32_16x16x32_bf16 v[96:99], v[96:99], v[100:103], 0
	s_waitcnt vmcnt(4)
	ds_bpermute_b32 v92, v78, v92
	ds_bpermute_b32 v93, v78, v93
	ds_bpermute_b32 v94, v78, v94
	v_mfma_f32_16x16x32_bf16 v[84:87], v[84:87], v[100:103], 0
	ds_bpermute_b32 v100, v78, v104
	ds_bpermute_b32 v101, v78, v105
	ds_bpermute_b32 v102, v78, v106
	ds_bpermute_b32 v103, v78, v107
	global_load_dwordx4 v[104:107], v[66:67], off
	s_waitcnt lgkmcnt(0)
	v_mfma_f32_16x16x32_bf16 v[18:21], v[88:91], v[100:103], v[18:21]
	ds_bpermute_b32 v88, v78, v112
	ds_bpermute_b32 v89, v78, v113
	ds_bpermute_b32 v90, v78, v114
	ds_bpermute_b32 v91, v78, v115
	global_load_dwordx4 v[112:115], v[76:77], off offset:2240
	global_load_dwordx4 v[136:139], v[24:25], off offset:2240
	s_waitcnt lgkmcnt(0)
	v_mfma_f32_16x16x32_bf16 v[88:91], v[88:91], v[100:103], v[108:111]
	ds_bpermute_b32 v95, v78, v95
	s_nop 1
	global_load_dwordx4 v[108:111], v[68:69], off
	v_add_u32_e32 v76, s3, v81
	s_waitcnt lgkmcnt(0)
	v_mfma_f32_16x16x32_bf16 v[92:95], v[92:95], v[100:103], v[96:99]
	s_nop 2
	ds_bpermute_b32 v96, v78, v116
	ds_bpermute_b32 v97, v78, v117
	ds_bpermute_b32 v98, v78, v118
	ds_bpermute_b32 v99, v78, v119
	global_load_dwordx4 v[116:119], v[70:71], off
	s_waitcnt lgkmcnt(0)
	v_mfma_f32_16x16x32_bf16 v[84:87], v[96:99], v[100:103], v[84:87]
	s_waitcnt vmcnt(8)
	ds_bpermute_b32 v100, v78, v120
	ds_bpermute_b32 v101, v78, v121
	ds_bpermute_b32 v102, v78, v122
	ds_bpermute_b32 v103, v78, v123
	global_load_dwordx4 v[120:123], v[72:73], off
	s_waitcnt vmcnt(8)
	ds_bpermute_b32 v96, v78, v124
	ds_bpermute_b32 v97, v78, v125
	ds_bpermute_b32 v98, v78, v126
	ds_bpermute_b32 v99, v78, v127
	s_waitcnt lgkmcnt(0)
	v_mfma_f32_16x16x32_bf16 v[18:21], v[96:99], v[100:103], v[18:21]
	s_waitcnt vmcnt(7)
	ds_bpermute_b32 v96, v78, v128
	ds_bpermute_b32 v97, v78, v129
	ds_bpermute_b32 v98, v78, v130
	ds_bpermute_b32 v99, v78, v131
	s_waitcnt lgkmcnt(0)
	v_mfma_f32_16x16x32_bf16 v[88:91], v[96:99], v[100:103], v[88:91]
	s_waitcnt vmcnt(6)
	ds_bpermute_b32 v96, v78, v132
	ds_bpermute_b32 v97, v78, v133
	ds_bpermute_b32 v98, v78, v134
	ds_bpermute_b32 v99, v78, v135
	s_waitcnt lgkmcnt(0)
	v_mfma_f32_16x16x32_bf16 v[92:95], v[96:99], v[100:103], v[92:95]
	s_waitcnt vmcnt(5)
	ds_bpermute_b32 v96, v78, v104
	ds_bpermute_b32 v97, v78, v105
	ds_bpermute_b32 v98, v78, v106
	ds_bpermute_b32 v99, v78, v107
	s_waitcnt lgkmcnt(0)
	v_mfma_f32_16x16x32_bf16 v[84:87], v[96:99], v[100:103], v[84:87]
	s_waitcnt vmcnt(3)
	ds_bpermute_b32 v96, v78, v136
	ds_bpermute_b32 v97, v78, v137
	ds_bpermute_b32 v98, v78, v138
	ds_bpermute_b32 v99, v78, v139
	ds_bpermute_b32 v100, v78, v112
	ds_bpermute_b32 v101, v78, v113
	ds_bpermute_b32 v102, v78, v114
	ds_bpermute_b32 v103, v78, v115
	s_waitcnt lgkmcnt(0)
	v_mfma_f32_16x16x32_bf16 v[18:21], v[96:99], v[100:103], v[18:21]
	s_waitcnt vmcnt(2)
	ds_bpermute_b32 v96, v78, v108
	ds_bpermute_b32 v97, v78, v109
	ds_bpermute_b32 v98, v78, v110
	ds_bpermute_b32 v99, v78, v111
	s_waitcnt lgkmcnt(0)
	v_mfma_f32_16x16x32_bf16 v[88:91], v[96:99], v[100:103], v[88:91]
	s_waitcnt vmcnt(1)
	ds_bpermute_b32 v96, v78, v116
	ds_bpermute_b32 v97, v78, v117
	ds_bpermute_b32 v98, v78, v118
	ds_bpermute_b32 v99, v78, v119
	s_waitcnt lgkmcnt(0)
	v_mfma_f32_16x16x32_bf16 v[92:95], v[96:99], v[100:103], v[92:95]
	s_waitcnt vmcnt(0)
	ds_bpermute_b32 v96, v78, v120
	ds_bpermute_b32 v97, v78, v121
	ds_bpermute_b32 v98, v78, v122
	ds_bpermute_b32 v99, v78, v123
	s_waitcnt lgkmcnt(0)
	v_mfma_f32_16x16x32_bf16 v[84:87], v[96:99], v[100:103], v[84:87]
	ds_write_b128 v76, v[14:17]
	ds_write_b128 v76, v[10:13] offset:1024
	ds_write_b128 v76, v[6:9] offset:2048
	ds_write_b128 v76, v[2:5] offset:3072
	ds_write_b128 v76, v[18:21] offset:4096
	ds_write_b128 v76, v[88:91] offset:5120
	ds_write_b128 v76, v[92:95] offset:6144
	s_nop 0
	ds_write_b128 v76, v[84:87] offset:7168
	s_waitcnt lgkmcnt(0)
	s_barrier
; __device__ __forceinline__ u32x2 pack4(const f32x4 v) { return (u32x2){cvtpk(v[0], v[1]), cvtpk(v[2], v[3])}; }
; __device__ __forceinline__ f32x4 unpack4(const u32x2 w) { return (f32x4){bflo(w.x), bfhi(w.x), bflo(w.y), bfhi(w.y)}; }
; template <int NPARTS, int STEPS  , bool FINAL, class Epi> ...
;     ...
;         f32x4 o = (f32x4){0.f, 0.f, 0.f, 0.f};
;         if (w < 4) {
;             f32x4 a2[NPARTS];
; #pragma unroll
;             for (int p = 0; p < NPARTS; ++p) { a2[p] = (f32x4){0.f, 0.f, 0.f, 0.f};
; #pragma unroll
;                 for (int w2 = 0; w2 < 8; ++w2) a2[p] += red[((w2 * NPARTS + p) * 4 + w) * 64 + lane]; }
;             const int row = MP + 16 * rg + fr, c0 = 64 * cg + 16 * w + 4 * fq;
;             o = E(row, c0, a2);
;             float s = (o[0] * o[0] + o[1] * o[1]) + (o[2] * o[2] + o[3] * o[3]);
;             s += __shfl_xor(s, 16); s += __shfl_xor(s, 32);
;             if (fq == 0) sred[w * 16 + fr] = s;
;         }
;     __device__ __forceinline__ f32x4 operator()(int row, int c0, const f32x4 (&acc)[2]) const {
;         bf16_t* pt = G + (size_t)row * 2048 + c0;
;         const f32x4 rho = unpack4(*(const u32x2*)pt), sgb = unpack4(*(const u32x2*)(pt + 1024));
;         const f32x4 m = sgb * (rho * acc[0] + acc[1]);
;         *(u32x2*)pt = pack4(m);
;         return m;
;     }
	s_cbranch_vccnz .LBB0_1389
	v_add_u32_e32 v2, s10, v79
	v_ashrrev_i32_e32 v3, 31, v2
	v_lshlrev_b64 v[2:3], 12, v[2:3]
	v_lshl_add_u64 v[76:77], v[74:75], 0, v[2:3]
	global_load_dwordx2 v[128:129], v[76:77], off
	global_load_dwordx2 v[130:131], v[76:77], off offset:2048
	v_add_u32_e32 v124, s12, v81
	ds_read_b128 v[2:5], v124
	ds_read_b128 v[6:9], v124 offset:4096
	ds_read_b128 v[10:13], v124 offset:8192
	ds_read_b128 v[14:17], v124 offset:12288
	ds_read_b128 v[18:21], v124 offset:16384
	ds_read_b128 v[84:87], v124 offset:20480
	ds_read_b128 v[88:91], v124 offset:24576
	ds_read_b128 v[92:95], v124 offset:28672
	ds_read_b128 v[96:99], v124 offset:32768
	ds_read_b128 v[100:103], v124 offset:36864
	ds_read_b128 v[104:107], v124 offset:40960
	ds_read_b128 v[108:111], v124 offset:45056
	ds_read_b128 v[112:115], v124 offset:49152
	ds_read_b128 v[116:119], v124 offset:53248
	ds_read_b128 v[120:123], v124 offset:57344
	ds_read_b128 v[124:127], v124 offset:61440
	s_waitcnt lgkmcnt(14)
	v_pk_add_f32 v[4:5], v[4:5], 0 op_sel_hi:[1,0]
	v_pk_add_f32 v[2:3], v[2:3], 0 op_sel_hi:[1,0]
	v_pk_add_f32 v[8:9], v[8:9], 0 op_sel_hi:[1,0]
	v_pk_add_f32 v[6:7], v[6:7], 0 op_sel_hi:[1,0]
	s_waitcnt lgkmcnt(13)
	v_pk_add_f32 v[4:5], v[12:13], v[4:5]
	v_pk_add_f32 v[2:3], v[10:11], v[2:3]
	s_waitcnt lgkmcnt(12)
	v_pk_add_f32 v[8:9], v[16:17], v[8:9]
	v_pk_add_f32 v[6:7], v[14:15], v[6:7]
	s_waitcnt lgkmcnt(11)
	v_pk_add_f32 v[4:5], v[20:21], v[4:5]
	v_pk_add_f32 v[2:3], v[18:19], v[2:3]
	s_waitcnt lgkmcnt(10)
	v_pk_add_f32 v[8:9], v[86:87], v[8:9]
	v_pk_add_f32 v[6:7], v[84:85], v[6:7]
	s_waitcnt lgkmcnt(9)
	v_pk_add_f32 v[4:5], v[90:91], v[4:5]
	v_pk_add_f32 v[2:3], v[88:89], v[2:3]
	s_waitcnt lgkmcnt(8)
	v_pk_add_f32 v[8:9], v[94:95], v[8:9]
	v_pk_add_f32 v[6:7], v[92:93], v[6:7]
	s_waitcnt lgkmcnt(7)
	v_pk_add_f32 v[4:5], v[98:99], v[4:5]
	v_pk_add_f32 v[2:3], v[96:97], v[2:3]
	s_waitcnt lgkmcnt(6)
	v_pk_add_f32 v[8:9], v[102:103], v[8:9]
	v_pk_add_f32 v[6:7], v[100:101], v[6:7]
	s_waitcnt lgkmcnt(5)
	v_pk_add_f32 v[4:5], v[106:107], v[4:5]
	v_pk_add_f32 v[2:3], v[104:105], v[2:3]
	s_waitcnt lgkmcnt(4)
	v_pk_add_f32 v[8:9], v[110:111], v[8:9]
	v_pk_add_f32 v[6:7], v[108:109], v[6:7]
	s_waitcnt lgkmcnt(3)
	v_pk_add_f32 v[4:5], v[114:115], v[4:5]
	v_pk_add_f32 v[2:3], v[112:113], v[2:3]
	s_waitcnt lgkmcnt(2)
	v_pk_add_f32 v[8:9], v[118:119], v[8:9]
	v_pk_add_f32 v[6:7], v[116:117], v[6:7]
	s_waitcnt lgkmcnt(1)
	v_pk_add_f32 v[4:5], v[122:123], v[4:5]
	v_pk_add_f32 v[2:3], v[120:121], v[2:3]
	s_waitcnt lgkmcnt(0)
	v_pk_add_f32 v[8:9], v[126:127], v[8:9]
	v_pk_add_f32 v[6:7], v[124:125], v[6:7]
	v_and_b32_e32 v133, 64, v83
	v_xor_b32_e32 v132, 16, v83
	v_add_u32_e32 v133, 64, v133
	v_cmp_lt_i32_e32 vcc, v132, v133
	s_waitcnt vmcnt(1)
	v_lshlrev_b32_e32 v10, 16, v128
	v_and_b32_e32 v11, 0xffff0000, v128
	v_lshlrev_b32_e32 v12, 16, v129
	v_and_b32_e32 v13, 0xffff0000, v129
	s_waitcnt vmcnt(0)
	v_lshlrev_b32_e32 v14, 16, v130
	v_and_b32_e32 v15, 0xffff0000, v130
	v_lshlrev_b32_e32 v16, 16, v131
	v_and_b32_e32 v17, 0xffff0000, v131
	v_pk_fma_f32 v[4:5], v[4:5], v[12:13], v[8:9]
	v_pk_fma_f32 v[2:3], v[2:3], v[10:11], v[6:7]
	v_pk_mul_f32 v[4:5], v[4:5], v[16:17]
	v_pk_mul_f32 v[6:7], v[2:3], v[14:15]
	v_mul_f32_e32 v3, v5, v5
	v_mul_f32_e32 v2, v7, v7
	v_cndmask_b32_e32 v132, v83, v132, vcc
	v_fmac_f32_e32 v2, v6, v6
	v_fmac_f32_e32 v3, v4, v4
	v_lshlrev_b32_e32 v132, 2, v132
	v_add_f32_e32 v2, v2, v3
	v_mov_b32_e32 v3, v2
	s_nop 1
	v_permlane16_swap_b32_e32 v2, v3
	v_xor_b32_e32 v8, 32, v83
	v_cmp_lt_i32_e32 vcc, v8, v133
	v_cvt_pk_bf16_f32 v6, v6, v7
	v_cvt_pk_bf16_f32 v7, v4, v5
	v_cndmask_b32_e32 v8, v83, v8, vcc
	s_waitcnt lgkmcnt(0)
	v_add_f32_e32 v2, v2, v3
	v_lshlrev_b32_e32 v3, 2, v8
	v_mov_b32_e32 v3, v2
	s_nop 1
	v_permlane32_swap_b32_e32 v2, v3
	global_store_dwordx2 v[76:77], v[6:7], off
	s_and_saveexec_b64 s[10:11], s[4:5]
	s_cbranch_execz .LBB0_1388
	s_waitcnt lgkmcnt(0)
	v_add_f32_e32 v2, v2, v3
	ds_write_b32 v82, v2
	s_branch .LBB0_1388

; #define SK_LOAD(b_, s0_) do { _Pragma("unroll") for (int u = 0; u < UB; ++u) if ((s0_) + u < STEPS) { af[b_][u] = *(const bf16x8*)(ap + ((s0_) + u) * 32); \
;                 _Pragma("unroll") for (int nt = 0; nt < 4; ++nt) wf[b_][u][nt] = *(const bf16x8*)(wp + (size_t)(16 * nt) * ldb + ((s0_) + u) * 32); } } while (0)
; #define SK_MMA(b_, s0_) do { _Pragma("unroll") for (int u = 0; u < UB; ++u) if ((s0_) + u < STEPS) { const bf16x8 afp = sk_perm(af[b_][u], pidx); \
;                 _Pragma("unroll") for (int nt = 0; nt < 4; ++nt) acc[p][nt] = __builtin_amdgcn_mfma_f32_16x16x32_bf16(sk_perm(wf[b_][u][nt], pidx), afp, acc[p][nt], 0, 0, 0); } } while (0)
; template <int NPARTS, int STEPS  , bool FINAL, class Epi> ...
;     ...
;         for (int p = 0; p < NPARTS; ++p) {
; #pragma unroll
;             for (int nt = 0; nt < 4; ++nt) acc[p][nt] = (f32x4){0.f, 0.f, 0.f, 0.f};
;             const bf16_t* wp = Bt + (size_t)(64 * cg + (lane >> 2)) * ldb + p * koff + w * (STEPS * 32) + 8 * (lane & 3);
;             const bf16_t* ap = A + (size_t)(MP + 16 * rg + (lane >> 2)) * lda + p * koff + w * (STEPS * 32) + 8 * (lane & 3);
;             constexpr int NB = (STEPS + UB - 1) / UB;
;             bf16x8 af[2][UB], wf[2][UB][4];
;     ...
;             SK_LOAD(0, 0);
; #pragma unroll
;             for (int b = 0; b < NB; ++b) {
;                 if (b + 1 < NB) { if ((b & 1) == 0) SK_LOAD(1, (b + 1) * UB); else SK_LOAD(0, (b + 1) * UB); }
;                 if ((b & 1) == 0) SK_MMA(0, b * UB); else SK_MMA(1, b * UB);
;             }
.LBB0_1490:
	s_and_b32 s6, s10, 15
	v_lshl_or_b32 v10, s6, 18, v31
	v_lshl_add_u64 v[16:17], v[12:13], 0, v[10:11]
	v_add_co_u32_e32 v20, vcc, 0x10000, v16
	s_and_b32 s7, s10, -16
	s_nop 0
	v_addc_co_u32_e32 v21, vcc, 0, v17, vcc
	v_add_co_u32_e32 v22, vcc, 0x20000, v16
	global_load_dwordx4 v[36:39], v[16:17], off
	global_load_dwordx4 v[40:43], v[16:17], off offset:64
	v_addc_co_u32_e32 v23, vcc, 0, v17, vcc
	v_add_u32_e32 v2, s7, v28
	global_load_dwordx4 v[44:47], v[16:17], off offset:128
	global_load_dwordx4 v[52:55], v[20:21], off
	global_load_dwordx4 v[60:63], v[22:23], off
	v_ashrrev_i32_e32 v3, 31, v2
	v_lshlrev_b64 v[2:3], 12, v[2:3]
	v_lshl_add_u64 v[24:25], v[14:15], 0, v[2:3]
	global_load_dwordx4 v[48:51], v[24:25], off
	global_load_dwordx4 v[56:59], v[24:25], off offset:64
	v_add_co_u32_e32 v18, vcc, 0x30000, v16
	s_waitcnt vmcnt(6)
	ds_bpermute_b32 v36, v26, v36
	v_addc_co_u32_e32 v19, vcc, 0, v17, vcc
	global_load_dwordx4 v[64:67], v[18:19], off
	global_load_dwordx4 v[68:71], v[20:21], off offset:64
	global_load_dwordx4 v[72:75], v[22:23], off offset:64
	global_load_dwordx4 v[76:79], v[18:19], off offset:64
	global_load_dwordx4 v[80:83], v[24:25], off offset:128
	global_load_dwordx4 v[84:87], v[20:21], off offset:128
	global_load_dwordx4 v[88:91], v[22:23], off offset:128
	global_load_dwordx4 v[92:95], v[16:17], off offset:192
	global_load_dwordx4 v[96:99], v[18:19], off offset:128
	global_load_dwordx4 v[100:103], v[24:25], off offset:192
	global_load_dwordx4 v[104:107], v[20:21], off offset:192
	global_load_dwordx4 v[6:9], v[22:23], off offset:192
	global_load_dwordx4 v[2:5], v[18:19], off offset:192
	ds_bpermute_b32 v37, v26, v37
	ds_bpermute_b32 v38, v26, v38
	ds_bpermute_b32 v39, v26, v39
	s_waitcnt vmcnt(16)
	ds_bpermute_b32 v52, v26, v52
	ds_bpermute_b32 v53, v26, v53
	ds_bpermute_b32 v54, v26, v54
	ds_bpermute_b32 v55, v26, v55
	s_waitcnt vmcnt(15)
	ds_bpermute_b32 v60, v26, v60
	ds_bpermute_b32 v61, v26, v61
	ds_bpermute_b32 v62, v26, v62
	ds_bpermute_b32 v63, v26, v63
	ds_bpermute_b32 v40, v26, v40
	ds_bpermute_b32 v41, v26, v41
	ds_bpermute_b32 v42, v26, v42
	ds_bpermute_b32 v43, v26, v43
	s_waitcnt vmcnt(14)
	ds_bpermute_b32 v48, v26, v48
	ds_bpermute_b32 v49, v26, v49
	ds_bpermute_b32 v50, v26, v50
	ds_bpermute_b32 v51, v26, v51
	s_waitcnt vmcnt(13)
	ds_bpermute_b32 v56, v26, v56
	ds_bpermute_b32 v57, v26, v57
	ds_bpermute_b32 v58, v26, v58
	ds_bpermute_b32 v59, v26, v59
	ds_bpermute_b32 v44, v26, v44
	ds_bpermute_b32 v45, v26, v45
	ds_bpermute_b32 v46, v26, v46
	s_waitcnt lgkmcnt(7)
	v_mfma_f32_16x16x32_bf16 v[36:39], v[36:39], v[48:51], 0
	ds_bpermute_b32 v47, v26, v47
	s_and_b64 vcc, exec, s[4:5]
	s_waitcnt vmcnt(12)
	ds_bpermute_b32 v64, v26, v64
	ds_bpermute_b32 v65, v26, v65
	ds_bpermute_b32 v66, v26, v66
	ds_bpermute_b32 v67, v26, v67
	s_waitcnt vmcnt(11)
	ds_bpermute_b32 v68, v26, v68
	ds_bpermute_b32 v69, v26, v69
	ds_bpermute_b32 v70, v26, v70
	ds_bpermute_b32 v71, v26, v71
	v_mfma_f32_16x16x32_bf16 v[52:55], v[52:55], v[48:51], 0
	s_waitcnt vmcnt(10)
	ds_bpermute_b32 v72, v26, v72
	ds_bpermute_b32 v73, v26, v73
	ds_bpermute_b32 v74, v26, v74
	v_mfma_f32_16x16x32_bf16 v[60:63], v[60:63], v[48:51], 0
	ds_bpermute_b32 v75, v26, v75
	s_waitcnt vmcnt(1)
	ds_bpermute_b32 v6, v26, v6
	ds_bpermute_b32 v7, v26, v7
	s_waitcnt lgkmcnt(10)
	v_mfma_f32_16x16x32_bf16 v[48:51], v[64:67], v[48:51], 0
	ds_bpermute_b32 v64, v26, v76
	ds_bpermute_b32 v65, v26, v77
	ds_bpermute_b32 v66, v26, v78
	ds_bpermute_b32 v67, v26, v79
	v_mfma_f32_16x16x32_bf16 v[36:39], v[40:43], v[56:59], v[36:39]
	global_load_dwordx4 v[76:79], v[18:19], off offset:2048
	ds_bpermute_b32 v8, v26, v8
	ds_bpermute_b32 v9, v26, v9
	s_waitcnt lgkmcnt(12)
	v_mfma_f32_16x16x32_bf16 v[40:43], v[68:71], v[56:59], v[52:55]
	ds_bpermute_b32 v68, v26, v84
	ds_bpermute_b32 v69, v26, v85
	ds_bpermute_b32 v70, v26, v86
	ds_bpermute_b32 v52, v26, v80
	ds_bpermute_b32 v53, v26, v81
	ds_bpermute_b32 v54, v26, v82
	ds_bpermute_b32 v55, v26, v83
	s_waitcnt lgkmcnt(14)
	v_mfma_f32_16x16x32_bf16 v[60:63], v[72:75], v[56:59], v[60:63]
	ds_bpermute_b32 v71, v26, v87
	ds_bpermute_b32 v72, v26, v100
	ds_bpermute_b32 v73, v26, v101
	s_waitcnt lgkmcnt(12)
	v_mfma_f32_16x16x32_bf16 v[48:51], v[64:67], v[56:59], v[48:51]
	global_load_dwordx4 v[56:59], v[16:17], off offset:2048
	global_load_dwordx4 v[64:67], v[24:25], off offset:2048
	global_load_dwordx4 v[80:83], v[24:25], off offset:2112
	s_waitcnt lgkmcnt(3)
	v_mfma_f32_16x16x32_bf16 v[36:39], v[44:47], v[52:55], v[36:39]
	ds_bpermute_b32 v44, v26, v88
	ds_bpermute_b32 v45, v26, v89
	ds_bpermute_b32 v46, v26, v90
	ds_bpermute_b32 v47, v26, v91
	s_waitcnt lgkmcnt(0)
	v_mfma_f32_16x16x32_bf16 v[44:47], v[44:47], v[52:55], v[60:63]
	s_nop 2
	ds_bpermute_b32 v60, v26, v96
	ds_bpermute_b32 v61, v26, v97
	ds_bpermute_b32 v62, v26, v98
	ds_bpermute_b32 v63, v26, v99
	v_mfma_f32_16x16x32_bf16 v[40:43], v[68:71], v[52:55], v[40:43]
	ds_bpermute_b32 v74, v26, v102
	ds_bpermute_b32 v75, v26, v103
	global_load_dwordx4 v[68:71], v[20:21], off offset:2048
	global_load_dwordx4 v[84:87], v[20:21], off offset:2112
	s_waitcnt lgkmcnt(2)
	v_mfma_f32_16x16x32_bf16 v[48:51], v[60:63], v[52:55], v[48:51]
	ds_bpermute_b32 v52, v26, v92
	ds_bpermute_b32 v53, v26, v93
	ds_bpermute_b32 v54, v26, v94
	ds_bpermute_b32 v55, v26, v95
	global_load_dwordx4 v[60:63], v[22:23], off offset:2048
	s_waitcnt lgkmcnt(0)
	v_mfma_f32_16x16x32_bf16 v[36:39], v[52:55], v[72:75], v[36:39]
	ds_bpermute_b32 v52, v26, v104
	ds_bpermute_b32 v53, v26, v105
	ds_bpermute_b32 v54, v26, v106
	ds_bpermute_b32 v55, v26, v107
	s_waitcnt lgkmcnt(0)
; #define SK_LOAD(b_, s0_) do { _Pragma("unroll") for (int u = 0; u < UB; ++u) if ((s0_) + u < STEPS) { af[b_][u] = *(const bf16x8*)(ap + ((s0_) + u) * 32); \
;                 _Pragma("unroll") for (int nt = 0; nt < 4; ++nt) wf[b_][u][nt] = *(const bf16x8*)(wp + (size_t)(16 * nt) * ldb + ((s0_) + u) * 32); } } while (0)
; #define SK_MMA(b_, s0_) do { _Pragma("unroll") for (int u = 0; u < UB; ++u) if ((s0_) + u < STEPS) { const bf16x8 afp = sk_perm(af[b_][u], pidx); \
;                 _Pragma("unroll") for (int nt = 0; nt < 4; ++nt) acc[p][nt] = __builtin_amdgcn_mfma_f32_16x16x32_bf16(sk_perm(wf[b_][u][nt], pidx), afp, acc[p][nt], 0, 0, 0); } } while (0)
; template <int NPARTS, int STEPS  , bool FINAL, class Epi> ...
;     ...
;             SK_LOAD(0, 0);
; #pragma unroll
;             for (int b = 0; b < NB; ++b) {
;                 if (b + 1 < NB) { if ((b & 1) == 0) SK_LOAD(1, (b + 1) * UB); else SK_LOAD(0, (b + 1) * UB); }
;                 if ((b & 1) == 0) SK_MMA(0, b * UB); else SK_MMA(1, b * UB);
;             }
;     ...
;         }
; #pragma unroll
;         for (int p = 0; p < NPARTS; ++p)
; #pragma unroll
;             for (int nt = 0; nt < 4; ++nt) red[((w * NPARTS + p) * 4 + nt) * 64 + lane] = acc[p][nt];
;         __syncthreads();
	v_mfma_f32_16x16x32_bf16 v[40:43], v[52:55], v[72:75], v[40:43]
	global_load_dwordx4 v[52:55], v[16:17], off offset:2112
	s_waitcnt vmcnt(8)
	ds_bpermute_b32 v2, v26, v2
	ds_bpermute_b32 v3, v26, v3
	v_mfma_f32_16x16x32_bf16 v[6:9], v[6:9], v[72:75], v[44:47]
	ds_bpermute_b32 v4, v26, v4
	ds_bpermute_b32 v5, v26, v5
	s_waitcnt vmcnt(3)
	ds_bpermute_b32 v68, v26, v68
	global_load_dwordx4 v[44:47], v[22:23], off offset:2112
	s_waitcnt lgkmcnt(1)
	v_mfma_f32_16x16x32_bf16 v[2:5], v[2:5], v[72:75], v[48:51]
	ds_bpermute_b32 v69, v26, v69
	ds_bpermute_b32 v70, v26, v70
	ds_bpermute_b32 v71, v26, v71
	ds_bpermute_b32 v48, v26, v56
	ds_bpermute_b32 v49, v26, v57
	ds_bpermute_b32 v50, v26, v58
	ds_bpermute_b32 v51, v26, v59
	ds_bpermute_b32 v56, v26, v64
	ds_bpermute_b32 v57, v26, v65
	ds_bpermute_b32 v58, v26, v66
	ds_bpermute_b32 v59, v26, v67
	global_load_dwordx4 v[64:67], v[18:19], off offset:2112
	global_load_dwordx4 v[72:75], v[24:25], off offset:2176
	global_load_dwordx4 v[88:91], v[16:17], off offset:2176
	global_load_dwordx4 v[92:95], v[20:21], off offset:2176
	s_waitcnt vmcnt(6)
	ds_bpermute_b32 v60, v26, v60
	ds_bpermute_b32 v61, v26, v61
	ds_bpermute_b32 v62, v26, v62
	ds_bpermute_b32 v63, v26, v63
	ds_bpermute_b32 v76, v26, v76
	ds_bpermute_b32 v77, v26, v77
	ds_bpermute_b32 v78, v26, v78
	ds_bpermute_b32 v79, v26, v79
	global_load_dwordx4 v[96:99], v[22:23], off offset:2176
	s_waitcnt lgkmcnt(8)
	v_mfma_f32_16x16x32_bf16 v[48:51], v[48:51], v[56:59], 0
	s_waitcnt vmcnt(6)
	ds_bpermute_b32 v52, v26, v52
	v_mfma_f32_16x16x32_bf16 v[68:71], v[68:71], v[56:59], 0
	ds_bpermute_b32 v53, v26, v53
	ds_bpermute_b32 v54, v26, v54
	ds_bpermute_b32 v55, v26, v55
	s_waitcnt lgkmcnt(8)
	v_mfma_f32_16x16x32_bf16 v[60:63], v[60:63], v[56:59], 0
	s_waitcnt vmcnt(5)
	ds_bpermute_b32 v44, v26, v44
	s_waitcnt lgkmcnt(5)
	v_mfma_f32_16x16x32_bf16 v[56:59], v[76:79], v[56:59], 0
	ds_bpermute_b32 v76, v26, v80
	ds_bpermute_b32 v77, v26, v81
	ds_bpermute_b32 v78, v26, v82
	ds_bpermute_b32 v79, v26, v83
	global_load_dwordx4 v[80:83], v[18:19], off offset:2176
	s_waitcnt lgkmcnt(0)
	v_mfma_f32_16x16x32_bf16 v[48:51], v[52:55], v[76:79], v[48:51]
	ds_bpermute_b32 v52, v26, v84
	ds_bpermute_b32 v53, v26, v85
	ds_bpermute_b32 v54, v26, v86
	ds_bpermute_b32 v55, v26, v87
	global_load_dwordx4 v[84:87], v[24:25], off offset:2240
	global_load_dwordx4 v[100:103], v[16:17], off offset:2240
	s_waitcnt lgkmcnt(0)
	v_mfma_f32_16x16x32_bf16 v[52:55], v[52:55], v[76:79], v[68:71]
	s_nop 2
	global_load_dwordx4 v[68:71], v[20:21], off offset:2240
	ds_bpermute_b32 v45, v26, v45
	global_load_dwordx4 v[16:19], v[18:19], off offset:2240
	ds_bpermute_b32 v46, v26, v46
	global_load_dwordx4 v[20:23], v[22:23], off offset:2240
	ds_bpermute_b32 v47, v26, v47
	s_waitcnt lgkmcnt(0)
	v_mfma_f32_16x16x32_bf16 v[44:47], v[44:47], v[76:79], v[60:63]
	s_waitcnt vmcnt(10)
	s_nop 1
	ds_bpermute_b32 v60, v26, v64
	ds_bpermute_b32 v61, v26, v65
	ds_bpermute_b32 v62, v26, v66
	ds_bpermute_b32 v63, v26, v67
	s_waitcnt lgkmcnt(0)
	v_mfma_f32_16x16x32_bf16 v[56:59], v[60:63], v[76:79], v[56:59]
	s_waitcnt vmcnt(8)
	ds_bpermute_b32 v60, v26, v88
	ds_bpermute_b32 v61, v26, v89
	ds_bpermute_b32 v62, v26, v90
	ds_bpermute_b32 v63, v26, v91
	ds_bpermute_b32 v64, v26, v72
	ds_bpermute_b32 v65, v26, v73
	ds_bpermute_b32 v66, v26, v74
	ds_bpermute_b32 v67, v26, v75
	s_waitcnt lgkmcnt(0)
	v_mfma_f32_16x16x32_bf16 v[48:51], v[60:63], v[64:67], v[48:51]
	s_waitcnt vmcnt(7)
	ds_bpermute_b32 v60, v26, v92
	ds_bpermute_b32 v61, v26, v93
	ds_bpermute_b32 v62, v26, v94
	ds_bpermute_b32 v63, v26, v95
	s_waitcnt lgkmcnt(0)
	v_mfma_f32_16x16x32_bf16 v[52:55], v[60:63], v[64:67], v[52:55]
	s_waitcnt vmcnt(6)
	ds_bpermute_b32 v60, v26, v96
	ds_bpermute_b32 v61, v26, v97
	ds_bpermute_b32 v62, v26, v98
	ds_bpermute_b32 v63, v26, v99
	s_waitcnt lgkmcnt(0)
	v_mfma_f32_16x16x32_bf16 v[44:47], v[60:63], v[64:67], v[44:47]
	s_waitcnt vmcnt(5)
	ds_bpermute_b32 v60, v26, v80
	ds_bpermute_b32 v61, v26, v81
	ds_bpermute_b32 v62, v26, v82
	ds_bpermute_b32 v63, v26, v83
	s_waitcnt lgkmcnt(0)
	v_mfma_f32_16x16x32_bf16 v[56:59], v[60:63], v[64:67], v[56:59]
	s_waitcnt vmcnt(3)
	ds_bpermute_b32 v60, v26, v100
	ds_bpermute_b32 v61, v26, v101
	ds_bpermute_b32 v62, v26, v102
	ds_bpermute_b32 v63, v26, v103
	ds_bpermute_b32 v64, v26, v84
	ds_bpermute_b32 v65, v26, v85
	ds_bpermute_b32 v66, v26, v86
	ds_bpermute_b32 v67, v26, v87
	s_waitcnt lgkmcnt(0)
	v_mfma_f32_16x16x32_bf16 v[48:51], v[60:63], v[64:67], v[48:51]
	s_waitcnt vmcnt(2)
	ds_bpermute_b32 v60, v26, v68
	ds_bpermute_b32 v61, v26, v69
	ds_bpermute_b32 v62, v26, v70
	ds_bpermute_b32 v63, v26, v71
	s_waitcnt vmcnt(0)
	ds_bpermute_b32 v20, v26, v20
	ds_bpermute_b32 v21, v26, v21
	ds_bpermute_b32 v22, v26, v22
	ds_bpermute_b32 v23, v26, v23
	ds_bpermute_b32 v16, v26, v16
	ds_bpermute_b32 v17, v26, v17
	ds_bpermute_b32 v18, v26, v18
	ds_bpermute_b32 v19, v26, v19
	s_waitcnt lgkmcnt(8)
	v_mfma_f32_16x16x32_bf16 v[52:55], v[60:63], v[64:67], v[52:55]
	s_waitcnt lgkmcnt(4)
	v_mfma_f32_16x16x32_bf16 v[20:23], v[20:23], v[64:67], v[44:47]
	s_waitcnt lgkmcnt(0)
	v_mfma_f32_16x16x32_bf16 v[16:19], v[16:19], v[64:67], v[56:59]
	ds_write_b128 v32, v[36:39]
	ds_write_b128 v32, v[40:43] offset:1024
	ds_write_b128 v32, v[6:9] offset:2048
	ds_write_b128 v32, v[2:5] offset:3072
	ds_write_b128 v32, v[48:51] offset:4096
	ds_write_b128 v32, v[52:55] offset:5120
	ds_write_b128 v32, v[20:23] offset:6144
	s_nop 0
	ds_write_b128 v32, v[16:19] offset:7168
	s_waitcnt lgkmcnt(0)
	s_barrier
; __device__ __forceinline__ u32x2 pack4(const f32x4 v) { return (u32x2){cvtpk(v[0], v[1]), cvtpk(v[2], v[3])}; }
; __device__ __forceinline__ f32x4 unpack4(const u32x2 w) { return (f32x4){bflo(w.x), bfhi(w.x), bflo(w.y), bfhi(w.y)}; }
; template <int NPARTS, int STEPS  , bool FINAL, class Epi> ...
;     ...
;         f32x4 o = (f32x4){0.f, 0.f, 0.f, 0.f};
;         if (w < 4) {
;             f32x4 a2[NPARTS];
; #pragma unroll
;             for (int p = 0; p < NPARTS; ++p) { a2[p] = (f32x4){0.f, 0.f, 0.f, 0.f};
; #pragma unroll
;                 for (int w2 = 0; w2 < 8; ++w2) a2[p] += red[((w2 * NPARTS + p) * 4 + w) * 64 + lane]; }
;             const int row = MP + 16 * rg + fr, c0 = 64 * cg + 16 * w + 4 * fq;
;             o = E(row, c0, a2);
;             float s = (o[0] * o[0] + o[1] * o[1]) + (o[2] * o[2] + o[3] * o[3]);
;             s += __shfl_xor(s, 16); s += __shfl_xor(s, 32);
;             if (fq == 0) sred[w * 16 + fr] = s;
;         }
;     __device__ __forceinline__ f32x4 operator()(int row, int c0, const f32x4 (&acc)[2]) const {
;         bf16_t* pt = G + (size_t)row * 2048 + c0;
;         const f32x4 rho = unpack4(*(const u32x2*)pt), sgb = unpack4(*(const u32x2*)(pt + 1024));
;         const f32x4 m = sgb * (rho * acc[0] + acc[1]);
;         *(u32x2*)pt = pack4(m);
;         return m;
;     }
	s_cbranch_vccnz .LBB0_1489
	v_add_u32_e32 v2, s7, v27
	v_ashrrev_i32_e32 v3, 31, v2
	v_lshlrev_b64 v[2:3], 12, v[2:3]
	v_lshl_add_u64 v[2:3], s[94:95], 0, v[2:3]
	v_lshl_or_b32 v10, s6, 7, v33
	v_lshl_add_u64 v[24:25], v[2:3], 0, v[10:11]
	global_load_dwordx2 v[84:85], v[24:25], off
	global_load_dwordx2 v[86:87], v[24:25], off offset:2048
	v_add_u32_e32 v10, s3, v29
	ds_read_b128 v[2:5], v10
	ds_read_b128 v[6:9], v10 offset:4096
	ds_read_b128 v[16:19], v10 offset:8192
	ds_read_b128 v[20:23], v10 offset:12288
	ds_read_b128 v[36:39], v10 offset:16384
	ds_read_b128 v[40:43], v10 offset:20480
	ds_read_b128 v[44:47], v10 offset:24576
	ds_read_b128 v[48:51], v10 offset:28672
	ds_read_b128 v[52:55], v10 offset:32768
	ds_read_b128 v[56:59], v10 offset:36864
	ds_read_b128 v[60:63], v10 offset:40960
	ds_read_b128 v[64:67], v10 offset:45056
	ds_read_b128 v[68:71], v10 offset:49152
	ds_read_b128 v[72:75], v10 offset:53248
	ds_read_b128 v[76:79], v10 offset:57344
	ds_read_b128 v[80:83], v10 offset:61440
	s_waitcnt lgkmcnt(14)
	v_pk_add_f32 v[4:5], v[4:5], 0 op_sel_hi:[1,0]
	v_pk_add_f32 v[2:3], v[2:3], 0 op_sel_hi:[1,0]
	v_pk_add_f32 v[8:9], v[8:9], 0 op_sel_hi:[1,0]
	v_pk_add_f32 v[6:7], v[6:7], 0 op_sel_hi:[1,0]
	s_waitcnt lgkmcnt(13)
	v_pk_add_f32 v[4:5], v[18:19], v[4:5]
	v_pk_add_f32 v[2:3], v[16:17], v[2:3]
	s_waitcnt lgkmcnt(12)
	v_pk_add_f32 v[8:9], v[22:23], v[8:9]
	v_pk_add_f32 v[6:7], v[20:21], v[6:7]
	s_waitcnt lgkmcnt(11)
	v_pk_add_f32 v[4:5], v[38:39], v[4:5]
	v_pk_add_f32 v[2:3], v[36:37], v[2:3]
	s_waitcnt lgkmcnt(10)
	v_pk_add_f32 v[8:9], v[42:43], v[8:9]
	v_pk_add_f32 v[6:7], v[40:41], v[6:7]
	s_waitcnt lgkmcnt(9)
	v_pk_add_f32 v[4:5], v[46:47], v[4:5]
	v_pk_add_f32 v[2:3], v[44:45], v[2:3]
	s_waitcnt lgkmcnt(8)
	v_pk_add_f32 v[8:9], v[50:51], v[8:9]
	v_pk_add_f32 v[6:7], v[48:49], v[6:7]
	s_waitcnt lgkmcnt(7)
	v_pk_add_f32 v[4:5], v[54:55], v[4:5]
	v_pk_add_f32 v[2:3], v[52:53], v[2:3]
	s_waitcnt lgkmcnt(6)
	v_pk_add_f32 v[8:9], v[58:59], v[8:9]
	v_pk_add_f32 v[6:7], v[56:57], v[6:7]
	s_waitcnt lgkmcnt(5)
	v_pk_add_f32 v[4:5], v[62:63], v[4:5]
	v_pk_add_f32 v[2:3], v[60:61], v[2:3]
	s_waitcnt lgkmcnt(4)
	v_pk_add_f32 v[8:9], v[66:67], v[8:9]
	v_pk_add_f32 v[6:7], v[64:65], v[6:7]
	s_waitcnt lgkmcnt(3)
	v_pk_add_f32 v[4:5], v[70:71], v[4:5]
	v_pk_add_f32 v[2:3], v[68:69], v[2:3]
	s_waitcnt lgkmcnt(2)
	v_pk_add_f32 v[8:9], v[74:75], v[8:9]
	v_pk_add_f32 v[6:7], v[72:73], v[6:7]
	s_waitcnt lgkmcnt(1)
	v_pk_add_f32 v[4:5], v[78:79], v[4:5]
	v_pk_add_f32 v[2:3], v[76:77], v[2:3]
	s_waitcnt lgkmcnt(0)
	v_pk_add_f32 v[8:9], v[82:83], v[8:9]
	v_pk_add_f32 v[6:7], v[80:81], v[6:7]
	v_and_b32_e32 v88, 64, v34
	v_xor_b32_e32 v35, 16, v34
	v_add_u32_e32 v10, 64, v88
	v_cmp_lt_i32_e32 vcc, v35, v10
	s_waitcnt vmcnt(1)
	v_lshlrev_b32_e32 v16, 16, v84
	v_and_b32_e32 v17, 0xffff0000, v84
	v_lshlrev_b32_e32 v18, 16, v85
	v_and_b32_e32 v19, 0xffff0000, v85
	s_waitcnt vmcnt(0)
	v_lshlrev_b32_e32 v20, 16, v86
	v_and_b32_e32 v21, 0xffff0000, v86
	v_lshlrev_b32_e32 v22, 16, v87
	v_and_b32_e32 v23, 0xffff0000, v87
	v_pk_fma_f32 v[4:5], v[4:5], v[18:19], v[8:9]
	v_pk_fma_f32 v[2:3], v[2:3], v[16:17], v[6:7]
	v_pk_mul_f32 v[4:5], v[4:5], v[22:23]
	v_pk_mul_f32 v[6:7], v[2:3], v[20:21]
	v_mul_f32_e32 v3, v5, v5
	v_mul_f32_e32 v2, v7, v7
	v_cndmask_b32_e32 v35, v34, v35, vcc
	v_fmac_f32_e32 v2, v6, v6
	v_fmac_f32_e32 v3, v4, v4
	v_lshlrev_b32_e32 v35, 2, v35
	v_add_f32_e32 v2, v2, v3
	v_mov_b32_e32 v3, v2
	s_nop 1
	v_permlane16_swap_b32_e32 v2, v3
	v_xor_b32_e32 v8, 32, v34
	v_cmp_lt_i32_e32 vcc, v8, v10
	v_cvt_pk_bf16_f32 v6, v6, v7
	v_cvt_pk_bf16_f32 v7, v4, v5
	v_cndmask_b32_e32 v8, v34, v8, vcc
	s_waitcnt lgkmcnt(0)
	v_add_f32_e32 v2, v2, v3
	v_lshlrev_b32_e32 v3, 2, v8
	v_mov_b32_e32 v3, v2
	s_nop 1
	v_permlane32_swap_b32_e32 v2, v3
	global_store_dwordx2 v[24:25], v[6:7], off
	s_and_saveexec_b64 s[6:7], s[0:1]
	s_cbranch_execz .LBB0_1488
	s_waitcnt lgkmcnt(0)
	v_add_f32_e32 v2, v2, v3
	ds_write_b32 v30, v2
	s_branch .LBB0_1488

; #define SK_LOAD(b_, s0_) do { _Pragma("unroll") for (int u = 0; u < UB; ++u) if ((s0_) + u < STEPS) { af[b_][u] = *(const bf16x8*)(ap + ((s0_) + u) * 32); \
;                 _Pragma("unroll") for (int nt = 0; nt < 4; ++nt) wf[b_][u][nt] = *(const bf16x8*)(wp + (size_t)(16 * nt) * ldb + ((s0_) + u) * 32); } } while (0)
; #define SK_MMA(b_, s0_) do { _Pragma("unroll") for (int u = 0; u < UB; ++u) if ((s0_) + u < STEPS) { const bf16x8 afp = sk_perm(af[b_][u], pidx); \
;                 _Pragma("unroll") for (int nt = 0; nt < 4; ++nt) acc[p][nt] = __builtin_amdgcn_mfma_f32_16x16x32_bf16(sk_perm(wf[b_][u][nt], pidx), afp, acc[p][nt], 0, 0, 0); } } while (0)
; template <int NPARTS, int STEPS  , bool FINAL, class Epi> ...
;     ...
;         for (int p = 0; p < NPARTS; ++p) {
; #pragma unroll
;             for (int nt = 0; nt < 4; ++nt) acc[p][nt] = (f32x4){0.f, 0.f, 0.f, 0.f};
;             const bf16_t* wp = Bt + (size_t)(64 * cg + (lane >> 2)) * ldb + p * koff + w * (STEPS * 32) + 8 * (lane & 3);
;             const bf16_t* ap = A + (size_t)(MP + 16 * rg + (lane >> 2)) * lda + p * koff + w * (STEPS * 32) + 8 * (lane & 3);
;             constexpr int NB = (STEPS + UB - 1) / UB;
;             bf16x8 af[2][UB], wf[2][UB][4];
;     ...
;             SK_LOAD(0, 0);
; #pragma unroll
;             for (int b = 0; b < NB; ++b) {
;                 if (b + 1 < NB) { if ((b & 1) == 0) SK_LOAD(1, (b + 1) * UB); else SK_LOAD(0, (b + 1) * UB); }
;                 if ((b & 1) == 0) SK_MMA(0, b * UB); else SK_MMA(1, b * UB);
;             }
.LBB0_1826:
	s_and_b32 s12, s22, 15
	s_lshl_b32 s14, s12, 6
	v_or_b32_e32 v2, s14, v85
	v_mul_u32_u24_e32 v2, 0xb00, v2
	v_lshlrev_b32_e32 v66, 1, v2
	v_lshl_add_u64 v[78:79], v[68:69], 0, v[66:67]
	v_add_co_u32_e32 v80, vcc, 0x16000, v78
	s_and_b32 s23, s22, -16
	s_nop 0
	v_addc_co_u32_e32 v81, vcc, 0, v79, vcc
	v_add_u32_e32 v3, s23, v86
	v_add_co_u32_e32 v76, vcc, 0x2c000, v78
	v_mad_i64_i32 v[74:75], s[24:25], v3, s3, v[70:71]
	s_nop 0
	v_addc_co_u32_e32 v77, vcc, 0, v79, vcc
	global_load_dwordx4 v[34:37], v[74:75], off
	global_load_dwordx4 v[92:95], v[74:75], off offset:64
	global_load_dwordx4 v[50:53], v[78:79], off
	global_load_dwordx4 v[18:21], v[74:75], off offset:128
	global_load_dwordx4 v[54:57], v[80:81], off
	global_load_dwordx4 v[96:99], v[78:79], off offset:64
	global_load_dwordx4 v[62:65], v[76:77], off
	v_add_co_u32_e32 v72, vcc, 0x42000, v78
	s_waitcnt vmcnt(6)
	ds_bpermute_b32 v34, v82, v34
	v_addc_co_u32_e32 v73, vcc, 0, v79, vcc
	global_load_dwordx4 v[58:61], v[72:73], off
	global_load_dwordx4 v[46:49], v[80:81], off offset:64
	global_load_dwordx4 v[42:45], v[76:77], off offset:64
	global_load_dwordx4 v[38:41], v[72:73], off offset:64
	global_load_dwordx4 v[30:33], v[78:79], off offset:128
	global_load_dwordx4 v[26:29], v[80:81], off offset:128
	global_load_dwordx4 v[10:13], v[74:75], off offset:192
	global_load_dwordx4 v[14:17], v[78:79], off offset:192
	global_load_dwordx4 v[22:25], v[76:77], off offset:128
	global_load_dwordx4 v[6:9], v[78:79], off offset:640
	global_load_dwordx4 v[100:103], v[80:81], off offset:192
	global_load_dwordx4 v[104:107], v[76:77], off offset:192
	global_load_dwordx4 v[2:5], v[80:81], off offset:640
	global_load_dwordx4 v[108:111], v[72:73], off offset:128
	s_waitcnt vmcnt(18)
	ds_bpermute_b32 v50, v82, v50
	ds_bpermute_b32 v51, v82, v51
	ds_bpermute_b32 v52, v82, v52
	ds_bpermute_b32 v53, v82, v53
	s_waitcnt vmcnt(16)
	ds_bpermute_b32 v54, v82, v54
	ds_bpermute_b32 v55, v82, v55
	ds_bpermute_b32 v56, v82, v56
	ds_bpermute_b32 v57, v82, v57
	s_waitcnt vmcnt(14)
	ds_bpermute_b32 v62, v82, v62
	ds_bpermute_b32 v63, v82, v63
	ds_bpermute_b32 v64, v82, v64
	ds_bpermute_b32 v65, v82, v65
	ds_bpermute_b32 v35, v82, v35
	ds_bpermute_b32 v36, v82, v36
	ds_bpermute_b32 v37, v82, v37
	ds_bpermute_b32 v92, v82, v92
	ds_bpermute_b32 v93, v82, v93
	ds_bpermute_b32 v94, v82, v94
	ds_bpermute_b32 v95, v82, v95
	s_waitcnt lgkmcnt(4)
	v_mfma_f32_16x16x32_bf16 v[50:53], v[50:53], v[34:37], 0
	ds_bpermute_b32 v96, v82, v96
	ds_bpermute_b32 v97, v82, v97
	ds_bpermute_b32 v98, v82, v98
	v_mfma_f32_16x16x32_bf16 v[54:57], v[54:57], v[34:37], 0
	ds_bpermute_b32 v99, v82, v99
	ds_bpermute_b32 v18, v82, v18
	ds_bpermute_b32 v19, v82, v19
	v_mfma_f32_16x16x32_bf16 v[62:65], v[62:65], v[34:37], 0
	ds_bpermute_b32 v20, v82, v20
	ds_bpermute_b32 v21, v82, v21
	s_and_b64 vcc, exec, s[8:9]
	s_waitcnt lgkmcnt(4)
	v_mfma_f32_16x16x32_bf16 v[50:53], v[96:99], v[92:95], v[50:53]
	s_waitcnt vmcnt(13)
	ds_bpermute_b32 v58, v82, v58
	ds_bpermute_b32 v59, v82, v59
	ds_bpermute_b32 v60, v82, v60
	ds_bpermute_b32 v61, v82, v61
	s_waitcnt vmcnt(10)
	ds_bpermute_b32 v38, v82, v38
	ds_bpermute_b32 v39, v82, v39
	ds_bpermute_b32 v40, v82, v40
	ds_bpermute_b32 v41, v82, v41
	s_waitcnt lgkmcnt(4)
	v_mfma_f32_16x16x32_bf16 v[34:37], v[58:61], v[34:37], 0
	ds_bpermute_b32 v46, v82, v46
	ds_bpermute_b32 v47, v82, v47
	ds_bpermute_b32 v48, v82, v48
	s_waitcnt lgkmcnt(3)
	v_mfma_f32_16x16x32_bf16 v[34:37], v[38:41], v[92:95], v[34:37]
	global_load_dwordx4 v[38:41], v[72:73], off offset:192
	ds_bpermute_b32 v49, v82, v49
	s_waitcnt vmcnt(10)
	ds_bpermute_b32 v30, v82, v30
	ds_bpermute_b32 v31, v82, v31
	ds_bpermute_b32 v32, v82, v32
	ds_bpermute_b32 v33, v82, v33
	s_waitcnt lgkmcnt(4)
	v_mfma_f32_16x16x32_bf16 v[46:49], v[46:49], v[92:95], v[54:57]
	s_waitcnt vmcnt(9)
	ds_bpermute_b32 v26, v82, v26
	ds_bpermute_b32 v27, v82, v27
	ds_bpermute_b32 v28, v82, v28
	s_waitcnt lgkmcnt(3)
	v_mfma_f32_16x16x32_bf16 v[30:33], v[30:33], v[18:21], v[50:53]
	ds_bpermute_b32 v29, v82, v29
	s_nop 1
	global_load_dwordx4 v[50:53], v[74:75], off offset:256
	global_load_dwordx4 v[54:57], v[78:79], off offset:256
	ds_bpermute_b32 v42, v82, v42
	ds_bpermute_b32 v43, v82, v43
	ds_bpermute_b32 v44, v82, v44
	ds_bpermute_b32 v45, v82, v45
	s_waitcnt lgkmcnt(4)
	v_mfma_f32_16x16x32_bf16 v[26:29], v[26:29], v[18:21], v[46:49]
	s_waitcnt vmcnt(8)
	ds_bpermute_b32 v22, v82, v22
	ds_bpermute_b32 v23, v82, v23
	ds_bpermute_b32 v24, v82, v24
	ds_bpermute_b32 v25, v82, v25
	global_load_dwordx4 v[46:49], v[80:81], off offset:256
	s_waitcnt lgkmcnt(4)
	v_mfma_f32_16x16x32_bf16 v[42:45], v[42:45], v[92:95], v[62:65]
	global_load_dwordx4 v[58:61], v[76:77], off offset:256
	ds_bpermute_b32 v14, v82, v14
	ds_bpermute_b32 v15, v82, v15
	s_waitcnt lgkmcnt(2)
	v_mfma_f32_16x16x32_bf16 v[22:25], v[22:25], v[18:21], v[42:45]
	ds_bpermute_b32 v16, v82, v16
	s_waitcnt vmcnt(5)
	s_nop 0
	ds_bpermute_b32 v42, v82, v108
	ds_bpermute_b32 v43, v82, v109
	ds_bpermute_b32 v44, v82, v110
	ds_bpermute_b32 v45, v82, v111
	s_waitcnt lgkmcnt(0)
	v_mfma_f32_16x16x32_bf16 v[18:21], v[42:45], v[18:21], v[34:37]
	s_nop 2
	global_load_dwordx4 v[34:37], v[72:73], off offset:256
	ds_bpermute_b32 v17, v82, v17
	ds_bpermute_b32 v10, v82, v10
	ds_bpermute_b32 v11, v82, v11
	ds_bpermute_b32 v12, v82, v12
	ds_bpermute_b32 v13, v82, v13
	s_waitcnt lgkmcnt(0)
	v_mfma_f32_16x16x32_bf16 v[14:17], v[14:17], v[10:13], v[30:33]
	s_nop 2
	ds_bpermute_b32 v30, v82, v100
	ds_bpermute_b32 v31, v82, v101
	ds_bpermute_b32 v32, v82, v102
	ds_bpermute_b32 v33, v82, v103
	global_load_dwordx4 v[42:45], v[74:75], off offset:320
	global_load_dwordx4 v[62:65], v[78:79], off offset:320
	s_waitcnt lgkmcnt(0)
; #define SK_LOAD(b_, s0_) do { _Pragma("unroll") for (int u = 0; u < UB; ++u) if ((s0_) + u < STEPS) { af[b_][u] = *(const bf16x8*)(ap + ((s0_) + u) * 32); \
;                 _Pragma("unroll") for (int nt = 0; nt < 4; ++nt) wf[b_][u][nt] = *(const bf16x8*)(wp + (size_t)(16 * nt) * ldb + ((s0_) + u) * 32); } } while (0)
; #define SK_MMA(b_, s0_) do { _Pragma("unroll") for (int u = 0; u < UB; ++u) if ((s0_) + u < STEPS) { const bf16x8 afp = sk_perm(af[b_][u], pidx); \
;                 _Pragma("unroll") for (int nt = 0; nt < 4; ++nt) acc[p][nt] = __builtin_amdgcn_mfma_f32_16x16x32_bf16(sk_perm(wf[b_][u][nt], pidx), afp, acc[p][nt], 0, 0, 0); } } while (0)
; template <int NPARTS, int STEPS  , bool FINAL, class Epi> ...
;     ...
;             SK_LOAD(0, 0);
; #pragma unroll
;             for (int b = 0; b < NB; ++b) {
;                 if (b + 1 < NB) { if ((b & 1) == 0) SK_LOAD(1, (b + 1) * UB); else SK_LOAD(0, (b + 1) * UB); }
;                 if ((b & 1) == 0) SK_MMA(0, b * UB); else SK_MMA(1, b * UB);
;             }
	v_mfma_f32_16x16x32_bf16 v[26:29], v[30:33], v[10:13], v[26:29]
	ds_bpermute_b32 v30, v82, v104
	ds_bpermute_b32 v31, v82, v105
	ds_bpermute_b32 v32, v82, v106
	ds_bpermute_b32 v33, v82, v107
	global_load_dwordx4 v[92:95], v[80:81], off offset:320
	s_waitcnt lgkmcnt(0)
	v_mfma_f32_16x16x32_bf16 v[22:25], v[30:33], v[10:13], v[22:25]
	s_waitcnt vmcnt(8)
	ds_bpermute_b32 v30, v82, v38
	ds_bpermute_b32 v31, v82, v39
	ds_bpermute_b32 v32, v82, v40
	ds_bpermute_b32 v33, v82, v41
	global_load_dwordx4 v[38:41], v[76:77], off offset:320
	s_waitcnt lgkmcnt(0)
	v_mfma_f32_16x16x32_bf16 v[10:13], v[30:33], v[10:13], v[18:21]
	s_waitcnt vmcnt(7)
	s_nop 1
	ds_bpermute_b32 v18, v82, v54
	ds_bpermute_b32 v19, v82, v55
	ds_bpermute_b32 v20, v82, v56
	ds_bpermute_b32 v21, v82, v57
	ds_bpermute_b32 v30, v82, v50
	ds_bpermute_b32 v31, v82, v51
	ds_bpermute_b32 v32, v82, v52
	ds_bpermute_b32 v33, v82, v53
	global_load_dwordx4 v[50:53], v[72:73], off offset:320
	s_waitcnt lgkmcnt(0)
	v_mfma_f32_16x16x32_bf16 v[14:17], v[18:21], v[30:33], v[14:17]
	s_waitcnt vmcnt(7)
	ds_bpermute_b32 v18, v82, v46
	ds_bpermute_b32 v19, v82, v47
	ds_bpermute_b32 v20, v82, v48
	ds_bpermute_b32 v21, v82, v49
	global_load_dwordx4 v[46:49], v[74:75], off offset:384
	global_load_dwordx4 v[54:57], v[78:79], off offset:384
	s_waitcnt lgkmcnt(0)
	v_mfma_f32_16x16x32_bf16 v[18:21], v[18:21], v[30:33], v[26:29]
	s_waitcnt vmcnt(8)
	s_nop 1
	ds_bpermute_b32 v26, v82, v58
	ds_bpermute_b32 v27, v82, v59
	ds_bpermute_b32 v28, v82, v60
	ds_bpermute_b32 v29, v82, v61
	global_load_dwordx4 v[58:61], v[80:81], off offset:384
	s_waitcnt lgkmcnt(0)
	v_mfma_f32_16x16x32_bf16 v[22:25], v[26:29], v[30:33], v[22:25]
	s_waitcnt vmcnt(8)
	ds_bpermute_b32 v26, v82, v34
	ds_bpermute_b32 v27, v82, v35
	ds_bpermute_b32 v28, v82, v36
	ds_bpermute_b32 v29, v82, v37
	global_load_dwordx4 v[34:37], v[76:77], off offset:384
	s_waitcnt lgkmcnt(0)
	v_mfma_f32_16x16x32_bf16 v[10:13], v[26:29], v[30:33], v[10:13]
	s_waitcnt vmcnt(8)
	ds_bpermute_b32 v30, v82, v42
	ds_bpermute_b32 v31, v82, v43
	ds_bpermute_b32 v32, v82, v44
	ds_bpermute_b32 v33, v82, v45
	global_load_dwordx4 v[42:45], v[72:73], off offset:384
	s_waitcnt vmcnt(8)
	ds_bpermute_b32 v26, v82, v62
	ds_bpermute_b32 v27, v82, v63
	ds_bpermute_b32 v28, v82, v64
	ds_bpermute_b32 v29, v82, v65
	s_waitcnt lgkmcnt(0)
	v_mfma_f32_16x16x32_bf16 v[14:17], v[26:29], v[30:33], v[14:17]
	s_waitcnt vmcnt(7)
	ds_bpermute_b32 v26, v82, v92
	ds_bpermute_b32 v27, v82, v93
	ds_bpermute_b32 v28, v82, v94
	ds_bpermute_b32 v29, v82, v95
	global_load_dwordx4 v[62:65], v[74:75], off offset:448
	global_load_dwordx4 v[92:95], v[78:79], off offset:448
	s_waitcnt lgkmcnt(0)
	v_mfma_f32_16x16x32_bf16 v[18:21], v[26:29], v[30:33], v[18:21]
	s_waitcnt vmcnt(8)
	ds_bpermute_b32 v26, v82, v38
	ds_bpermute_b32 v27, v82, v39
	ds_bpermute_b32 v28, v82, v40
	ds_bpermute_b32 v29, v82, v41
	global_load_dwordx4 v[38:41], v[80:81], off offset:448
	s_waitcnt lgkmcnt(0)
	v_mfma_f32_16x16x32_bf16 v[22:25], v[26:29], v[30:33], v[22:25]
	s_waitcnt vmcnt(8)
	ds_bpermute_b32 v26, v82, v50
	ds_bpermute_b32 v27, v82, v51
	ds_bpermute_b32 v28, v82, v52
	ds_bpermute_b32 v29, v82, v53
	global_load_dwordx4 v[50:53], v[76:77], off offset:448
	s_waitcnt lgkmcnt(0)
	v_mfma_f32_16x16x32_bf16 v[10:13], v[26:29], v[30:33], v[10:13]
	s_waitcnt vmcnt(7)
	ds_bpermute_b32 v26, v82, v54
	ds_bpermute_b32 v27, v82, v55
	ds_bpermute_b32 v28, v82, v56
	ds_bpermute_b32 v29, v82, v57
	ds_bpermute_b32 v30, v82, v46
	ds_bpermute_b32 v31, v82, v47
	ds_bpermute_b32 v32, v82, v48
	ds_bpermute_b32 v33, v82, v49
	global_load_dwordx4 v[46:49], v[72:73], off offset:448
	s_waitcnt lgkmcnt(0)
	v_mfma_f32_16x16x32_bf16 v[14:17], v[26:29], v[30:33], v[14:17]
	s_waitcnt vmcnt(7)
	ds_bpermute_b32 v26, v82, v58
	ds_bpermute_b32 v27, v82, v59
	ds_bpermute_b32 v28, v82, v60
	ds_bpermute_b32 v29, v82, v61
	global_load_dwordx4 v[54:57], v[74:75], off offset:512
	global_load_dwordx4 v[58:61], v[78:79], off offset:512
	s_waitcnt lgkmcnt(0)
	v_mfma_f32_16x16x32_bf16 v[18:21], v[26:29], v[30:33], v[18:21]
	s_waitcnt vmcnt(8)
	ds_bpermute_b32 v26, v82, v34
	ds_bpermute_b32 v27, v82, v35
	ds_bpermute_b32 v28, v82, v36
	ds_bpermute_b32 v29, v82, v37
	global_load_dwordx4 v[34:37], v[80:81], off offset:512
	s_waitcnt lgkmcnt(0)
	v_mfma_f32_16x16x32_bf16 v[22:25], v[26:29], v[30:33], v[22:25]
	s_waitcnt vmcnt(8)
	ds_bpermute_b32 v26, v82, v42
	ds_bpermute_b32 v27, v82, v43
	ds_bpermute_b32 v28, v82, v44
	ds_bpermute_b32 v29, v82, v45
	global_load_dwordx4 v[42:45], v[76:77], off offset:512
	s_waitcnt lgkmcnt(0)
	v_mfma_f32_16x16x32_bf16 v[10:13], v[26:29], v[30:33], v[10:13]
	s_waitcnt vmcnt(8)
	ds_bpermute_b32 v30, v82, v62
	ds_bpermute_b32 v31, v82, v63
	ds_bpermute_b32 v32, v82, v64
	ds_bpermute_b32 v33, v82, v65
	global_load_dwordx4 v[62:65], v[72:73], off offset:512
	s_waitcnt vmcnt(8)
	ds_bpermute_b32 v26, v82, v92
	ds_bpermute_b32 v27, v82, v93
	ds_bpermute_b32 v28, v82, v94
	ds_bpermute_b32 v29, v82, v95
	s_waitcnt lgkmcnt(0)
	v_mfma_f32_16x16x32_bf16 v[14:17], v[26:29], v[30:33], v[14:17]
	s_waitcnt vmcnt(7)
	ds_bpermute_b32 v26, v82, v38
	ds_bpermute_b32 v27, v82, v39
	ds_bpermute_b32 v28, v82, v40
	ds_bpermute_b32 v29, v82, v41
	global_load_dwordx4 v[38:41], v[74:75], off offset:576
	global_load_dwordx4 v[92:95], v[78:79], off offset:576
	s_waitcnt lgkmcnt(0)
	v_mfma_f32_16x16x32_bf16 v[18:21], v[26:29], v[30:33], v[18:21]
	s_waitcnt vmcnt(8)
	ds_bpermute_b32 v26, v82, v50
	ds_bpermute_b32 v27, v82, v51
	ds_bpermute_b32 v28, v82, v52
	ds_bpermute_b32 v29, v82, v53
	s_waitcnt lgkmcnt(0)
	v_mfma_f32_16x16x32_bf16 v[22:25], v[26:29], v[30:33], v[22:25]
	s_waitcnt vmcnt(7)
; __device__ __forceinline__ u32x2 pack4(const f32x4 v) { return (u32x2){cvtpk(v[0], v[1]), cvtpk(v[2], v[3])}; }
; __device__ __forceinline__ f32x4 unpack4(const u32x2 w) { return (f32x4){bflo(w.x), bfhi(w.x), bflo(w.y), bfhi(w.y)}; }
; template <int NPARTS, int STEPS  , bool FINAL, class Epi> ...
;     ...
; #pragma unroll
;         for (int p = 0; p < NPARTS; ++p)
; #pragma unroll
;             for (int nt = 0; nt < 4; ++nt) red[((w * NPARTS + p) * 4 + nt) * 64 + lane] = acc[p][nt];
;         __syncthreads();
;         f32x4 o = (f32x4){0.f, 0.f, 0.f, 0.f};
;         if (w < 4) {
;             f32x4 a2[NPARTS];
; #pragma unroll
;             for (int p = 0; p < NPARTS; ++p) { a2[p] = (f32x4){0.f, 0.f, 0.f, 0.f};
; #pragma unroll
;                 for (int w2 = 0; w2 < 8; ++w2) a2[p] += red[((w2 * NPARTS + p) * 4 + w) * 64 + lane]; }
;             const int row = MP + 16 * rg + fr, c0 = 64 * cg + 16 * w + 4 * fq;
;             o = E(row, c0, a2);
;             float s = (o[0] * o[0] + o[1] * o[1]) + (o[2] * o[2] + o[3] * o[3]);
;             s += __shfl_xor(s, 16); s += __shfl_xor(s, 32);
;             if (fq == 0) sred[w * 16 + fr] = s;
;         }
;     __device__ __forceinline__ f32x4 operator()(int row, int c0, const f32x4 (&acc)[1]) const {
;         const size_t off = (size_t)row * D + c0;
;         f32x4 b;
;         if (BASE_BF16) b = unpack4(*(const u32x2*)((const bf16_t*)base + off)); else b = *(const f32x4*)((const float*)base + (off - (size_t)MP * D));
;         const f32x4 v = b + acc[0] * scale;
;         if (OUT_F32) *(f32x4*)(outf + off) = v;
;         if (OUT_BF16) *(u32x2*)(outb + off) = pack4(v);
;         return v;
;     }
	ds_bpermute_b32 v26, v82, v46
	ds_bpermute_b32 v27, v82, v47
	ds_bpermute_b32 v28, v82, v48
	ds_bpermute_b32 v29, v82, v49
	s_waitcnt lgkmcnt(0)
	v_mfma_f32_16x16x32_bf16 v[10:13], v[26:29], v[30:33], v[10:13]
	s_waitcnt vmcnt(5)
	ds_bpermute_b32 v26, v82, v58
	ds_bpermute_b32 v27, v82, v59
	ds_bpermute_b32 v28, v82, v60
	ds_bpermute_b32 v29, v82, v61
	global_load_dwordx4 v[50:53], v[80:81], off offset:576
	ds_bpermute_b32 v30, v82, v54
	ds_bpermute_b32 v31, v82, v55
	ds_bpermute_b32 v32, v82, v56
	ds_bpermute_b32 v33, v82, v57
	s_waitcnt lgkmcnt(0)
	v_mfma_f32_16x16x32_bf16 v[14:17], v[26:29], v[30:33], v[14:17]
	s_waitcnt vmcnt(5)
	ds_bpermute_b32 v26, v82, v34
	ds_bpermute_b32 v27, v82, v35
	ds_bpermute_b32 v28, v82, v36
	ds_bpermute_b32 v29, v82, v37
	global_load_dwordx4 v[46:49], v[76:77], off offset:576
	global_load_dwordx4 v[34:37], v[74:75], off offset:640
	s_waitcnt lgkmcnt(0)
	v_mfma_f32_16x16x32_bf16 v[18:21], v[26:29], v[30:33], v[18:21]
	s_waitcnt vmcnt(6)
	ds_bpermute_b32 v26, v82, v42
	ds_bpermute_b32 v27, v82, v43
	ds_bpermute_b32 v28, v82, v44
	ds_bpermute_b32 v29, v82, v45
	global_load_dwordx4 v[54:57], v[72:73], off offset:576
	s_waitcnt lgkmcnt(0)
	v_mfma_f32_16x16x32_bf16 v[22:25], v[26:29], v[30:33], v[22:25]
	s_waitcnt vmcnt(6)
	ds_bpermute_b32 v26, v82, v62
	ds_bpermute_b32 v27, v82, v63
	ds_bpermute_b32 v28, v82, v64
	ds_bpermute_b32 v29, v82, v65
	global_load_dwordx4 v[42:45], v[76:77], off offset:640
	s_waitcnt lgkmcnt(0)
	v_mfma_f32_16x16x32_bf16 v[10:13], v[26:29], v[30:33], v[10:13]
	s_waitcnt vmcnt(6)
	ds_bpermute_b32 v30, v82, v38
	ds_bpermute_b32 v31, v82, v39
	ds_bpermute_b32 v32, v82, v40
	ds_bpermute_b32 v33, v82, v41
	global_load_dwordx4 v[38:41], v[72:73], off offset:640
	s_waitcnt vmcnt(6)
	ds_bpermute_b32 v26, v82, v92
	ds_bpermute_b32 v27, v82, v93
	ds_bpermute_b32 v28, v82, v94
	ds_bpermute_b32 v29, v82, v95
	s_waitcnt lgkmcnt(0)
	v_mfma_f32_16x16x32_bf16 v[14:17], v[26:29], v[30:33], v[14:17]
	ds_bpermute_b32 v6, v82, v6
	ds_bpermute_b32 v7, v82, v7
	ds_bpermute_b32 v8, v82, v8
	ds_bpermute_b32 v9, v82, v9
	ds_bpermute_b32 v2, v82, v2
	ds_bpermute_b32 v3, v82, v3
	ds_bpermute_b32 v4, v82, v4
	ds_bpermute_b32 v5, v82, v5
	s_waitcnt vmcnt(5)
	ds_bpermute_b32 v26, v82, v50
	ds_bpermute_b32 v27, v82, v51
	ds_bpermute_b32 v28, v82, v52
	ds_bpermute_b32 v29, v82, v53
	s_waitcnt lgkmcnt(0)
	v_mfma_f32_16x16x32_bf16 v[18:21], v[26:29], v[30:33], v[18:21]
	s_waitcnt vmcnt(4)
	ds_bpermute_b32 v26, v82, v46
	ds_bpermute_b32 v27, v82, v47
	ds_bpermute_b32 v28, v82, v48
	ds_bpermute_b32 v29, v82, v49
	s_waitcnt lgkmcnt(0)
	v_mfma_f32_16x16x32_bf16 v[22:25], v[26:29], v[30:33], v[22:25]
	s_waitcnt vmcnt(2)
	ds_bpermute_b32 v26, v82, v54
	ds_bpermute_b32 v27, v82, v55
	ds_bpermute_b32 v28, v82, v56
	ds_bpermute_b32 v29, v82, v57
	s_waitcnt lgkmcnt(0)
	v_mfma_f32_16x16x32_bf16 v[10:13], v[26:29], v[30:33], v[10:13]
	ds_bpermute_b32 v26, v82, v34
	ds_bpermute_b32 v27, v82, v35
	ds_bpermute_b32 v28, v82, v36
	ds_bpermute_b32 v29, v82, v37
	s_waitcnt lgkmcnt(0)
	v_mfma_f32_16x16x32_bf16 v[6:9], v[6:9], v[26:29], v[14:17]
	s_waitcnt vmcnt(1)
	s_nop 1
	ds_bpermute_b32 v14, v82, v42
	ds_bpermute_b32 v15, v82, v43
	ds_bpermute_b32 v16, v82, v44
	ds_bpermute_b32 v17, v82, v45
	v_mfma_f32_16x16x32_bf16 v[2:5], v[2:5], v[26:29], v[18:21]
	s_waitcnt vmcnt(0)
	s_nop 1
	ds_bpermute_b32 v18, v82, v38
	ds_bpermute_b32 v19, v82, v39
	ds_bpermute_b32 v20, v82, v40
	ds_bpermute_b32 v21, v82, v41
	s_waitcnt lgkmcnt(4)
	v_mfma_f32_16x16x32_bf16 v[14:17], v[14:17], v[26:29], v[22:25]
	s_waitcnt lgkmcnt(0)
	v_mfma_f32_16x16x32_bf16 v[10:13], v[18:21], v[26:29], v[10:13]
	ds_write_b128 v90, v[6:9]
	ds_write_b128 v90, v[2:5] offset:1024
	s_nop 3
	ds_write_b128 v90, v[14:17] offset:2048
	s_nop 0
	ds_write_b128 v90, v[10:13] offset:3072
	s_waitcnt lgkmcnt(0)
	s_barrier
	s_cbranch_vccnz .LBB0_1830
	v_add_u32_e32 v2, s23, v83
	v_ashrrev_i32_e32 v3, 31, v2
	v_lshlrev_b64 v[34:35], 10, v[2:3]
	v_or3_b32 v34, v89, s14, v34
	v_lshl_add_u64 v[2:3], v[34:35], 1, s[40:41]
	global_load_dwordx2 v[36:37], v[2:3], off
	ds_read_b128 v[2:5], v87
	ds_read_b128 v[6:9], v87 offset:4096
	ds_read_b128 v[10:13], v87 offset:8192
	ds_read_b128 v[14:17], v87 offset:12288
	ds_read_b128 v[18:21], v87 offset:16384
	ds_read_b128 v[22:25], v87 offset:20480
	ds_read_b128 v[26:29], v87 offset:24576
	ds_read_b128 v[30:33], v87 offset:28672
	s_waitcnt lgkmcnt(7)
	v_pk_add_f32 v[4:5], v[4:5], 0 op_sel_hi:[1,0]
	v_pk_add_f32 v[2:3], v[2:3], 0 op_sel_hi:[1,0]
	s_waitcnt lgkmcnt(6)
	v_pk_add_f32 v[4:5], v[4:5], v[8:9]
	v_pk_add_f32 v[2:3], v[2:3], v[6:7]
	s_waitcnt lgkmcnt(5)
	v_pk_add_f32 v[4:5], v[4:5], v[12:13]
	v_pk_add_f32 v[2:3], v[2:3], v[10:11]
	s_waitcnt lgkmcnt(4)
	v_pk_add_f32 v[4:5], v[4:5], v[16:17]
	v_pk_add_f32 v[2:3], v[2:3], v[14:15]
	s_waitcnt lgkmcnt(3)
	v_pk_add_f32 v[4:5], v[4:5], v[20:21]
	v_pk_add_f32 v[2:3], v[2:3], v[18:19]
	s_waitcnt lgkmcnt(2)
	v_pk_add_f32 v[4:5], v[4:5], v[24:25]
	v_pk_add_f32 v[2:3], v[2:3], v[22:23]
	s_waitcnt lgkmcnt(1)
	v_pk_add_f32 v[4:5], v[4:5], v[28:29]
	v_pk_add_f32 v[2:3], v[2:3], v[26:27]
	v_and_b32_e32 v39, 64, v91
	s_waitcnt lgkmcnt(0)
	v_pk_add_f32 v[4:5], v[4:5], v[32:33]
	v_pk_add_f32 v[2:3], v[2:3], v[30:31]
	v_xor_b32_e32 v38, 16, v91
	v_add_u32_e32 v39, 64, v39
	v_cmp_lt_i32_e32 vcc, v38, v39
	s_waitcnt vmcnt(0)
	v_lshlrev_b32_e32 v8, 16, v36
	v_and_b32_e32 v9, 0xffff0000, v36
	v_lshlrev_b32_e32 v6, 16, v37
	v_and_b32_e32 v7, 0xffff0000, v37
	v_pk_fma_f32 v[6:7], v[4:5], 0.5, v[6:7] op_sel_hi:[1,0,1]
	v_pk_fma_f32 v[4:5], v[2:3], 0.5, v[8:9] op_sel_hi:[1,0,1]
	v_mul_f32_e32 v3, v7, v7
	v_mul_f32_e32 v2, v5, v5
	v_cndmask_b32_e32 v38, v91, v38, vcc
	v_fmac_f32_e32 v2, v4, v4
	v_fmac_f32_e32 v3, v6, v6
	v_lshlrev_b32_e32 v38, 2, v38
	v_add_f32_e32 v2, v2, v3
	v_mov_b32_e32 v3, v2
	s_nop 1
	v_permlane16_swap_b32_e32 v2, v3
	v_xor_b32_e32 v8, 32, v91
	v_cmp_lt_i32_e32 vcc, v8, v39
	s_waitcnt lgkmcnt(0)
	v_add_f32_e32 v2, v2, v3
	v_cndmask_b32_e32 v8, v91, v8, vcc
	v_lshlrev_b32_e32 v3, 2, v8
	v_mov_b32_e32 v3, v2
	s_nop 1
	v_permlane32_swap_b32_e32 v2, v3
	v_lshl_add_u64 v[8:9], v[34:35], 2, s[92:93]
	global_store_dwordx4 v[8:9], v[4:7], off
	s_and_saveexec_b64 s[14:15], s[4:5]
	s_cbranch_execz .LBB0_1829
	s_waitcnt lgkmcnt(0)
	v_add_f32_e32 v2, v2, v3
	ds_write_b32 v88, v2 offset:32768

; #define SK_LOAD(b_, s0_) do { _Pragma("unroll") for (int u = 0; u < UB; ++u) if ((s0_) + u < STEPS) { af[b_][u] = *(const bf16x8*)(ap + ((s0_) + u) * 32); \
;                 _Pragma("unroll") for (int nt = 0; nt < 4; ++nt) wf[b_][u][nt] = *(const bf16x8*)(wp + (size_t)(16 * nt) * ldb + ((s0_) + u) * 32); } } while (0)
; #define SK_MMA(b_, s0_) do { _Pragma("unroll") for (int u = 0; u < UB; ++u) if ((s0_) + u < STEPS) { const bf16x8 afp = sk_perm(af[b_][u], pidx); \
;                 _Pragma("unroll") for (int nt = 0; nt < 4; ++nt) acc[p][nt] = __builtin_amdgcn_mfma_f32_16x16x32_bf16(sk_perm(wf[b_][u][nt], pidx), afp, acc[p][nt], 0, 0, 0); } } while (0)
; template <int NPARTS, int STEPS  , bool FINAL, class Epi> ...
;     ...
;         for (int p = 0; p < NPARTS; ++p) {
; #pragma unroll
;             for (int nt = 0; nt < 4; ++nt) acc[p][nt] = (f32x4){0.f, 0.f, 0.f, 0.f};
;             const bf16_t* wp = Bt + (size_t)(64 * cg + (lane >> 2)) * ldb + p * koff + w * (STEPS * 32) + 8 * (lane & 3);
;             const bf16_t* ap = A + (size_t)(MP + 16 * rg + (lane >> 2)) * lda + p * koff + w * (STEPS * 32) + 8 * (lane & 3);
;             constexpr int NB = (STEPS + UB - 1) / UB;
;             bf16x8 af[2][UB], wf[2][UB][4];
;     ...
;             SK_LOAD(0, 0);
; #pragma unroll
;             for (int b = 0; b < NB; ++b) {
;                 if (b + 1 < NB) { if ((b & 1) == 0) SK_LOAD(1, (b + 1) * UB); else SK_LOAD(0, (b + 1) * UB); }
;                 if ((b & 1) == 0) SK_MMA(0, b * UB); else SK_MMA(1, b * UB);
;             }
.LBB0_1934:
	s_and_b32 s10, s36, 15
	s_lshl_b32 s12, s10, 6
	v_or_b32_e32 v2, s12, v85
	v_mul_u32_u24_e32 v2, 0xb00, v2
	v_lshlrev_b32_e32 v66, 1, v2
	v_lshl_add_u64 v[78:79], v[68:69], 0, v[66:67]
	v_add_co_u32_e32 v80, vcc, 0x16000, v78
	s_and_b32 s14, s36, -16
	s_nop 0
	v_addc_co_u32_e32 v81, vcc, 0, v79, vcc
	v_add_u32_e32 v3, s14, v86
	v_add_co_u32_e32 v76, vcc, 0x2c000, v78
	v_mad_i64_i32 v[74:75], s[22:23], v3, s33, v[70:71]
	s_nop 0
	v_addc_co_u32_e32 v77, vcc, 0, v79, vcc
	global_load_dwordx4 v[34:37], v[74:75], off
	global_load_dwordx4 v[94:97], v[74:75], off offset:64
	global_load_dwordx4 v[50:53], v[78:79], off
	global_load_dwordx4 v[18:21], v[74:75], off offset:128
	global_load_dwordx4 v[54:57], v[80:81], off
	global_load_dwordx4 v[98:101], v[78:79], off offset:64
	global_load_dwordx4 v[62:65], v[76:77], off
	v_add_co_u32_e32 v72, vcc, 0x42000, v78
	s_waitcnt vmcnt(6)
	ds_bpermute_b32 v34, v82, v34
	v_addc_co_u32_e32 v73, vcc, 0, v79, vcc
	global_load_dwordx4 v[58:61], v[72:73], off
	global_load_dwordx4 v[46:49], v[80:81], off offset:64
	global_load_dwordx4 v[42:45], v[76:77], off offset:64
	global_load_dwordx4 v[38:41], v[72:73], off offset:64
	global_load_dwordx4 v[30:33], v[78:79], off offset:128
	global_load_dwordx4 v[26:29], v[80:81], off offset:128
	global_load_dwordx4 v[10:13], v[74:75], off offset:192
	global_load_dwordx4 v[14:17], v[78:79], off offset:192
	global_load_dwordx4 v[22:25], v[76:77], off offset:128
	global_load_dwordx4 v[6:9], v[78:79], off offset:640
	global_load_dwordx4 v[102:105], v[80:81], off offset:192
	global_load_dwordx4 v[106:109], v[76:77], off offset:192
	global_load_dwordx4 v[2:5], v[80:81], off offset:640
	global_load_dwordx4 v[110:113], v[72:73], off offset:128
	s_waitcnt vmcnt(18)
	ds_bpermute_b32 v50, v82, v50
	ds_bpermute_b32 v51, v82, v51
	ds_bpermute_b32 v52, v82, v52
	ds_bpermute_b32 v53, v82, v53
	s_waitcnt vmcnt(16)
	ds_bpermute_b32 v54, v82, v54
	ds_bpermute_b32 v55, v82, v55
	ds_bpermute_b32 v56, v82, v56
	ds_bpermute_b32 v57, v82, v57
	s_waitcnt vmcnt(14)
	ds_bpermute_b32 v62, v82, v62
	ds_bpermute_b32 v63, v82, v63
	ds_bpermute_b32 v64, v82, v64
	ds_bpermute_b32 v65, v82, v65
	ds_bpermute_b32 v35, v82, v35
	ds_bpermute_b32 v36, v82, v36
	ds_bpermute_b32 v37, v82, v37
	ds_bpermute_b32 v94, v82, v94
	ds_bpermute_b32 v95, v82, v95
	ds_bpermute_b32 v96, v82, v96
	ds_bpermute_b32 v97, v82, v97
	s_waitcnt lgkmcnt(4)
	v_mfma_f32_16x16x32_bf16 v[50:53], v[50:53], v[34:37], 0
	ds_bpermute_b32 v98, v82, v98
	ds_bpermute_b32 v99, v82, v99
	ds_bpermute_b32 v100, v82, v100
	v_mfma_f32_16x16x32_bf16 v[54:57], v[54:57], v[34:37], 0
	ds_bpermute_b32 v101, v82, v101
	ds_bpermute_b32 v18, v82, v18
	ds_bpermute_b32 v19, v82, v19
	v_mfma_f32_16x16x32_bf16 v[62:65], v[62:65], v[34:37], 0
	ds_bpermute_b32 v20, v82, v20
	ds_bpermute_b32 v21, v82, v21
	s_and_b64 vcc, exec, s[8:9]
	s_waitcnt lgkmcnt(4)
	v_mfma_f32_16x16x32_bf16 v[50:53], v[98:101], v[94:97], v[50:53]
	s_waitcnt vmcnt(13)
	ds_bpermute_b32 v58, v82, v58
	ds_bpermute_b32 v59, v82, v59
	ds_bpermute_b32 v60, v82, v60
	ds_bpermute_b32 v61, v82, v61
	s_waitcnt vmcnt(10)
	ds_bpermute_b32 v38, v82, v38
	ds_bpermute_b32 v39, v82, v39
	ds_bpermute_b32 v40, v82, v40
	ds_bpermute_b32 v41, v82, v41
	s_waitcnt lgkmcnt(4)
	v_mfma_f32_16x16x32_bf16 v[34:37], v[58:61], v[34:37], 0
	ds_bpermute_b32 v46, v82, v46
	ds_bpermute_b32 v47, v82, v47
	ds_bpermute_b32 v48, v82, v48
	s_waitcnt lgkmcnt(3)
	v_mfma_f32_16x16x32_bf16 v[34:37], v[38:41], v[94:97], v[34:37]
	global_load_dwordx4 v[38:41], v[72:73], off offset:192
	ds_bpermute_b32 v49, v82, v49
	s_waitcnt vmcnt(10)
	ds_bpermute_b32 v30, v82, v30
	ds_bpermute_b32 v31, v82, v31
	ds_bpermute_b32 v32, v82, v32
	ds_bpermute_b32 v33, v82, v33
	s_waitcnt lgkmcnt(4)
	v_mfma_f32_16x16x32_bf16 v[46:49], v[46:49], v[94:97], v[54:57]
	s_waitcnt vmcnt(9)
	ds_bpermute_b32 v26, v82, v26
	ds_bpermute_b32 v27, v82, v27
	ds_bpermute_b32 v28, v82, v28
	s_waitcnt lgkmcnt(3)
	v_mfma_f32_16x16x32_bf16 v[30:33], v[30:33], v[18:21], v[50:53]
	ds_bpermute_b32 v29, v82, v29
	s_nop 1
	global_load_dwordx4 v[50:53], v[74:75], off offset:256
	global_load_dwordx4 v[54:57], v[78:79], off offset:256
	ds_bpermute_b32 v42, v82, v42
	ds_bpermute_b32 v43, v82, v43
	ds_bpermute_b32 v44, v82, v44
	ds_bpermute_b32 v45, v82, v45
	s_waitcnt lgkmcnt(4)
	v_mfma_f32_16x16x32_bf16 v[26:29], v[26:29], v[18:21], v[46:49]
	s_waitcnt vmcnt(8)
	ds_bpermute_b32 v22, v82, v22
	ds_bpermute_b32 v23, v82, v23
	ds_bpermute_b32 v24, v82, v24
	ds_bpermute_b32 v25, v82, v25
	global_load_dwordx4 v[46:49], v[80:81], off offset:256
	s_waitcnt lgkmcnt(4)
	v_mfma_f32_16x16x32_bf16 v[42:45], v[42:45], v[94:97], v[62:65]
	global_load_dwordx4 v[58:61], v[76:77], off offset:256
	ds_bpermute_b32 v14, v82, v14
	ds_bpermute_b32 v15, v82, v15
	s_waitcnt lgkmcnt(2)
	v_mfma_f32_16x16x32_bf16 v[22:25], v[22:25], v[18:21], v[42:45]
	ds_bpermute_b32 v16, v82, v16
	s_waitcnt vmcnt(5)
	s_nop 0
	ds_bpermute_b32 v42, v82, v110
	ds_bpermute_b32 v43, v82, v111
	ds_bpermute_b32 v44, v82, v112
	ds_bpermute_b32 v45, v82, v113
	s_waitcnt lgkmcnt(0)
	v_mfma_f32_16x16x32_bf16 v[18:21], v[42:45], v[18:21], v[34:37]
	s_nop 2
	global_load_dwordx4 v[34:37], v[72:73], off offset:256
	ds_bpermute_b32 v17, v82, v17
	ds_bpermute_b32 v10, v82, v10
	ds_bpermute_b32 v11, v82, v11
	ds_bpermute_b32 v12, v82, v12
	ds_bpermute_b32 v13, v82, v13
	s_waitcnt lgkmcnt(0)
	v_mfma_f32_16x16x32_bf16 v[14:17], v[14:17], v[10:13], v[30:33]
	s_nop 2
	ds_bpermute_b32 v30, v82, v102
	ds_bpermute_b32 v31, v82, v103
	ds_bpermute_b32 v32, v82, v104
	ds_bpermute_b32 v33, v82, v105
	global_load_dwordx4 v[42:45], v[74:75], off offset:320
	global_load_dwordx4 v[62:65], v[78:79], off offset:320
	s_waitcnt lgkmcnt(0)
; #define SK_LOAD(b_, s0_) do { _Pragma("unroll") for (int u = 0; u < UB; ++u) if ((s0_) + u < STEPS) { af[b_][u] = *(const bf16x8*)(ap + ((s0_) + u) * 32); \
;                 _Pragma("unroll") for (int nt = 0; nt < 4; ++nt) wf[b_][u][nt] = *(const bf16x8*)(wp + (size_t)(16 * nt) * ldb + ((s0_) + u) * 32); } } while (0)
; #define SK_MMA(b_, s0_) do { _Pragma("unroll") for (int u = 0; u < UB; ++u) if ((s0_) + u < STEPS) { const bf16x8 afp = sk_perm(af[b_][u], pidx); \
;                 _Pragma("unroll") for (int nt = 0; nt < 4; ++nt) acc[p][nt] = __builtin_amdgcn_mfma_f32_16x16x32_bf16(sk_perm(wf[b_][u][nt], pidx), afp, acc[p][nt], 0, 0, 0); } } while (0)
; template <int NPARTS, int STEPS  , bool FINAL, class Epi> ...
;     ...
;             SK_LOAD(0, 0);
; #pragma unroll
;             for (int b = 0; b < NB; ++b) {
;                 if (b + 1 < NB) { if ((b & 1) == 0) SK_LOAD(1, (b + 1) * UB); else SK_LOAD(0, (b + 1) * UB); }
;                 if ((b & 1) == 0) SK_MMA(0, b * UB); else SK_MMA(1, b * UB);
;             }
	v_mfma_f32_16x16x32_bf16 v[26:29], v[30:33], v[10:13], v[26:29]
	ds_bpermute_b32 v30, v82, v106
	ds_bpermute_b32 v31, v82, v107
	ds_bpermute_b32 v32, v82, v108
	ds_bpermute_b32 v33, v82, v109
	global_load_dwordx4 v[94:97], v[80:81], off offset:320
	s_waitcnt lgkmcnt(0)
	v_mfma_f32_16x16x32_bf16 v[22:25], v[30:33], v[10:13], v[22:25]
	s_waitcnt vmcnt(8)
	ds_bpermute_b32 v30, v82, v38
	ds_bpermute_b32 v31, v82, v39
	ds_bpermute_b32 v32, v82, v40
	ds_bpermute_b32 v33, v82, v41
	global_load_dwordx4 v[38:41], v[76:77], off offset:320
	s_waitcnt lgkmcnt(0)
	v_mfma_f32_16x16x32_bf16 v[10:13], v[30:33], v[10:13], v[18:21]
	s_waitcnt vmcnt(7)
	s_nop 1
	ds_bpermute_b32 v18, v82, v54
	ds_bpermute_b32 v19, v82, v55
	ds_bpermute_b32 v20, v82, v56
	ds_bpermute_b32 v21, v82, v57
	ds_bpermute_b32 v30, v82, v50
	ds_bpermute_b32 v31, v82, v51
	ds_bpermute_b32 v32, v82, v52
	ds_bpermute_b32 v33, v82, v53
	global_load_dwordx4 v[50:53], v[72:73], off offset:320
	s_waitcnt lgkmcnt(0)
	v_mfma_f32_16x16x32_bf16 v[14:17], v[18:21], v[30:33], v[14:17]
	s_waitcnt vmcnt(7)
	ds_bpermute_b32 v18, v82, v46
	ds_bpermute_b32 v19, v82, v47
	ds_bpermute_b32 v20, v82, v48
	ds_bpermute_b32 v21, v82, v49
	global_load_dwordx4 v[46:49], v[74:75], off offset:384
	global_load_dwordx4 v[54:57], v[78:79], off offset:384
	s_waitcnt lgkmcnt(0)
	v_mfma_f32_16x16x32_bf16 v[18:21], v[18:21], v[30:33], v[26:29]
	s_waitcnt vmcnt(8)
	s_nop 1
	ds_bpermute_b32 v26, v82, v58
	ds_bpermute_b32 v27, v82, v59
	ds_bpermute_b32 v28, v82, v60
	ds_bpermute_b32 v29, v82, v61
	global_load_dwordx4 v[58:61], v[80:81], off offset:384
	s_waitcnt lgkmcnt(0)
	v_mfma_f32_16x16x32_bf16 v[22:25], v[26:29], v[30:33], v[22:25]
	s_waitcnt vmcnt(8)
	ds_bpermute_b32 v26, v82, v34
	ds_bpermute_b32 v27, v82, v35
	ds_bpermute_b32 v28, v82, v36
	ds_bpermute_b32 v29, v82, v37
	global_load_dwordx4 v[34:37], v[76:77], off offset:384
	s_waitcnt lgkmcnt(0)
	v_mfma_f32_16x16x32_bf16 v[10:13], v[26:29], v[30:33], v[10:13]
	s_waitcnt vmcnt(8)
	ds_bpermute_b32 v30, v82, v42
	ds_bpermute_b32 v31, v82, v43
	ds_bpermute_b32 v32, v82, v44
	ds_bpermute_b32 v33, v82, v45
	global_load_dwordx4 v[42:45], v[72:73], off offset:384
	s_waitcnt vmcnt(8)
	ds_bpermute_b32 v26, v82, v62
	ds_bpermute_b32 v27, v82, v63
	ds_bpermute_b32 v28, v82, v64
	ds_bpermute_b32 v29, v82, v65
	s_waitcnt lgkmcnt(0)
	v_mfma_f32_16x16x32_bf16 v[14:17], v[26:29], v[30:33], v[14:17]
	s_waitcnt vmcnt(7)
	ds_bpermute_b32 v26, v82, v94
	ds_bpermute_b32 v27, v82, v95
	ds_bpermute_b32 v28, v82, v96
	ds_bpermute_b32 v29, v82, v97
	global_load_dwordx4 v[62:65], v[74:75], off offset:448
	global_load_dwordx4 v[94:97], v[78:79], off offset:448
	s_waitcnt lgkmcnt(0)
	v_mfma_f32_16x16x32_bf16 v[18:21], v[26:29], v[30:33], v[18:21]
	s_waitcnt vmcnt(8)
	ds_bpermute_b32 v26, v82, v38
	ds_bpermute_b32 v27, v82, v39
	ds_bpermute_b32 v28, v82, v40
	ds_bpermute_b32 v29, v82, v41
	global_load_dwordx4 v[38:41], v[80:81], off offset:448
	s_waitcnt lgkmcnt(0)
	v_mfma_f32_16x16x32_bf16 v[22:25], v[26:29], v[30:33], v[22:25]
	s_waitcnt vmcnt(8)
	ds_bpermute_b32 v26, v82, v50
	ds_bpermute_b32 v27, v82, v51
	ds_bpermute_b32 v28, v82, v52
	ds_bpermute_b32 v29, v82, v53
	global_load_dwordx4 v[50:53], v[76:77], off offset:448
	s_waitcnt lgkmcnt(0)
	v_mfma_f32_16x16x32_bf16 v[10:13], v[26:29], v[30:33], v[10:13]
	s_waitcnt vmcnt(7)
	ds_bpermute_b32 v26, v82, v54
	ds_bpermute_b32 v27, v82, v55
	ds_bpermute_b32 v28, v82, v56
	ds_bpermute_b32 v29, v82, v57
	ds_bpermute_b32 v30, v82, v46
	ds_bpermute_b32 v31, v82, v47
	ds_bpermute_b32 v32, v82, v48
	ds_bpermute_b32 v33, v82, v49
	global_load_dwordx4 v[46:49], v[72:73], off offset:448
	s_waitcnt lgkmcnt(0)
	v_mfma_f32_16x16x32_bf16 v[14:17], v[26:29], v[30:33], v[14:17]
	s_waitcnt vmcnt(7)
	ds_bpermute_b32 v26, v82, v58
	ds_bpermute_b32 v27, v82, v59
	ds_bpermute_b32 v28, v82, v60
	ds_bpermute_b32 v29, v82, v61
	global_load_dwordx4 v[54:57], v[74:75], off offset:512
	global_load_dwordx4 v[58:61], v[78:79], off offset:512
	s_waitcnt lgkmcnt(0)
	v_mfma_f32_16x16x32_bf16 v[18:21], v[26:29], v[30:33], v[18:21]
	s_waitcnt vmcnt(8)
	ds_bpermute_b32 v26, v82, v34
	ds_bpermute_b32 v27, v82, v35
	ds_bpermute_b32 v28, v82, v36
	ds_bpermute_b32 v29, v82, v37
	global_load_dwordx4 v[34:37], v[80:81], off offset:512
	s_waitcnt lgkmcnt(0)
	v_mfma_f32_16x16x32_bf16 v[22:25], v[26:29], v[30:33], v[22:25]
	s_waitcnt vmcnt(8)
	ds_bpermute_b32 v26, v82, v42
	ds_bpermute_b32 v27, v82, v43
	ds_bpermute_b32 v28, v82, v44
	ds_bpermute_b32 v29, v82, v45
	global_load_dwordx4 v[42:45], v[76:77], off offset:512
	s_waitcnt lgkmcnt(0)
	v_mfma_f32_16x16x32_bf16 v[10:13], v[26:29], v[30:33], v[10:13]
	s_waitcnt vmcnt(8)
	ds_bpermute_b32 v30, v82, v62
	ds_bpermute_b32 v31, v82, v63
	ds_bpermute_b32 v32, v82, v64
	ds_bpermute_b32 v33, v82, v65
	global_load_dwordx4 v[62:65], v[72:73], off offset:512
	s_waitcnt vmcnt(8)
	ds_bpermute_b32 v26, v82, v94
	ds_bpermute_b32 v27, v82, v95
	ds_bpermute_b32 v28, v82, v96
	ds_bpermute_b32 v29, v82, v97
	s_waitcnt lgkmcnt(0)
	v_mfma_f32_16x16x32_bf16 v[14:17], v[26:29], v[30:33], v[14:17]
	s_waitcnt vmcnt(7)
	ds_bpermute_b32 v26, v82, v38
	ds_bpermute_b32 v27, v82, v39
	ds_bpermute_b32 v28, v82, v40
	ds_bpermute_b32 v29, v82, v41
	global_load_dwordx4 v[38:41], v[74:75], off offset:576
	global_load_dwordx4 v[94:97], v[78:79], off offset:576
	s_waitcnt lgkmcnt(0)
	v_mfma_f32_16x16x32_bf16 v[18:21], v[26:29], v[30:33], v[18:21]
	s_waitcnt vmcnt(8)
	ds_bpermute_b32 v26, v82, v50
	ds_bpermute_b32 v27, v82, v51
	ds_bpermute_b32 v28, v82, v52
	ds_bpermute_b32 v29, v82, v53
	s_waitcnt lgkmcnt(0)
	v_mfma_f32_16x16x32_bf16 v[22:25], v[26:29], v[30:33], v[22:25]
	s_waitcnt vmcnt(7)
; __device__ __forceinline__ u32x2 pack4(const f32x4 v) { return (u32x2){cvtpk(v[0], v[1]), cvtpk(v[2], v[3])}; }
; __device__ __forceinline__ f32x4 unpack4(const u32x2 w) { return (f32x4){bflo(w.x), bfhi(w.x), bflo(w.y), bfhi(w.y)}; }
; template <int NPARTS, int STEPS  , bool FINAL, class Epi> ...
;     ...
; #pragma unroll
;         for (int p = 0; p < NPARTS; ++p)
; #pragma unroll
;             for (int nt = 0; nt < 4; ++nt) red[((w * NPARTS + p) * 4 + nt) * 64 + lane] = acc[p][nt];
;         __syncthreads();
;         f32x4 o = (f32x4){0.f, 0.f, 0.f, 0.f};
;         if (w < 4) {
;             f32x4 a2[NPARTS];
; #pragma unroll
;             for (int p = 0; p < NPARTS; ++p) { a2[p] = (f32x4){0.f, 0.f, 0.f, 0.f};
; #pragma unroll
;                 for (int w2 = 0; w2 < 8; ++w2) a2[p] += red[((w2 * NPARTS + p) * 4 + w) * 64 + lane]; }
;             const int row = MP + 16 * rg + fr, c0 = 64 * cg + 16 * w + 4 * fq;
;             o = E(row, c0, a2);
;             float s = (o[0] * o[0] + o[1] * o[1]) + (o[2] * o[2] + o[3] * o[3]);
;             s += __shfl_xor(s, 16); s += __shfl_xor(s, 32);
;             if (fq == 0) sred[w * 16 + fr] = s;
;         }
;     __device__ __forceinline__ f32x4 operator()(int row, int c0, const f32x4 (&acc)[1]) const {
;         const size_t off = (size_t)row * D + c0;
;         f32x4 b;
;         if (BASE_BF16) b = unpack4(*(const u32x2*)((const bf16_t*)base + off)); else b = *(const f32x4*)((const float*)base + (off - (size_t)MP * D));
;         const f32x4 v = b + acc[0] * scale;
;         if (OUT_F32) *(f32x4*)(outf + off) = v;
;         if (OUT_BF16) *(u32x2*)(outb + off) = pack4(v);
;         return v;
;     }
	ds_bpermute_b32 v26, v82, v46
	ds_bpermute_b32 v27, v82, v47
	ds_bpermute_b32 v28, v82, v48
	ds_bpermute_b32 v29, v82, v49
	s_waitcnt lgkmcnt(0)
	v_mfma_f32_16x16x32_bf16 v[10:13], v[26:29], v[30:33], v[10:13]
	s_waitcnt vmcnt(5)
	ds_bpermute_b32 v26, v82, v58
	ds_bpermute_b32 v27, v82, v59
	ds_bpermute_b32 v28, v82, v60
	ds_bpermute_b32 v29, v82, v61
	global_load_dwordx4 v[50:53], v[80:81], off offset:576
	ds_bpermute_b32 v30, v82, v54
	ds_bpermute_b32 v31, v82, v55
	ds_bpermute_b32 v32, v82, v56
	ds_bpermute_b32 v33, v82, v57
	s_waitcnt lgkmcnt(0)
	v_mfma_f32_16x16x32_bf16 v[14:17], v[26:29], v[30:33], v[14:17]
	s_waitcnt vmcnt(5)
	ds_bpermute_b32 v26, v82, v34
	ds_bpermute_b32 v27, v82, v35
	ds_bpermute_b32 v28, v82, v36
	ds_bpermute_b32 v29, v82, v37
	global_load_dwordx4 v[46:49], v[76:77], off offset:576
	global_load_dwordx4 v[34:37], v[74:75], off offset:640
	s_waitcnt lgkmcnt(0)
	v_mfma_f32_16x16x32_bf16 v[18:21], v[26:29], v[30:33], v[18:21]
	s_waitcnt vmcnt(6)
	ds_bpermute_b32 v26, v82, v42
	ds_bpermute_b32 v27, v82, v43
	ds_bpermute_b32 v28, v82, v44
	ds_bpermute_b32 v29, v82, v45
	global_load_dwordx4 v[54:57], v[72:73], off offset:576
	s_waitcnt lgkmcnt(0)
	v_mfma_f32_16x16x32_bf16 v[22:25], v[26:29], v[30:33], v[22:25]
	s_waitcnt vmcnt(6)
	ds_bpermute_b32 v26, v82, v62
	ds_bpermute_b32 v27, v82, v63
	ds_bpermute_b32 v28, v82, v64
	ds_bpermute_b32 v29, v82, v65
	global_load_dwordx4 v[42:45], v[76:77], off offset:640
	s_waitcnt lgkmcnt(0)
	v_mfma_f32_16x16x32_bf16 v[10:13], v[26:29], v[30:33], v[10:13]
	s_waitcnt vmcnt(6)
	ds_bpermute_b32 v30, v82, v38
	ds_bpermute_b32 v31, v82, v39
	ds_bpermute_b32 v32, v82, v40
	ds_bpermute_b32 v33, v82, v41
	global_load_dwordx4 v[38:41], v[72:73], off offset:640
	s_waitcnt vmcnt(6)
	ds_bpermute_b32 v26, v82, v94
	ds_bpermute_b32 v27, v82, v95
	ds_bpermute_b32 v28, v82, v96
	ds_bpermute_b32 v29, v82, v97
	s_waitcnt lgkmcnt(0)
	v_mfma_f32_16x16x32_bf16 v[14:17], v[26:29], v[30:33], v[14:17]
	ds_bpermute_b32 v6, v82, v6
	ds_bpermute_b32 v7, v82, v7
	ds_bpermute_b32 v8, v82, v8
	ds_bpermute_b32 v9, v82, v9
	ds_bpermute_b32 v2, v82, v2
	ds_bpermute_b32 v3, v82, v3
	ds_bpermute_b32 v4, v82, v4
	ds_bpermute_b32 v5, v82, v5
	s_waitcnt vmcnt(5)
	ds_bpermute_b32 v26, v82, v50
	ds_bpermute_b32 v27, v82, v51
	ds_bpermute_b32 v28, v82, v52
	ds_bpermute_b32 v29, v82, v53
	s_waitcnt lgkmcnt(0)
	v_mfma_f32_16x16x32_bf16 v[18:21], v[26:29], v[30:33], v[18:21]
	s_waitcnt vmcnt(4)
	ds_bpermute_b32 v26, v82, v46
	ds_bpermute_b32 v27, v82, v47
	ds_bpermute_b32 v28, v82, v48
	ds_bpermute_b32 v29, v82, v49
	s_waitcnt lgkmcnt(0)
	v_mfma_f32_16x16x32_bf16 v[22:25], v[26:29], v[30:33], v[22:25]
	s_waitcnt vmcnt(2)
	ds_bpermute_b32 v26, v82, v54
	ds_bpermute_b32 v27, v82, v55
	ds_bpermute_b32 v28, v82, v56
	ds_bpermute_b32 v29, v82, v57
	s_waitcnt lgkmcnt(0)
	v_mfma_f32_16x16x32_bf16 v[10:13], v[26:29], v[30:33], v[10:13]
	ds_bpermute_b32 v26, v82, v34
	ds_bpermute_b32 v27, v82, v35
	ds_bpermute_b32 v28, v82, v36
	ds_bpermute_b32 v29, v82, v37
	s_waitcnt lgkmcnt(0)
	v_mfma_f32_16x16x32_bf16 v[6:9], v[6:9], v[26:29], v[14:17]
	s_waitcnt vmcnt(1)
	s_nop 1
	ds_bpermute_b32 v14, v82, v42
	ds_bpermute_b32 v15, v82, v43
	ds_bpermute_b32 v16, v82, v44
	ds_bpermute_b32 v17, v82, v45
	v_mfma_f32_16x16x32_bf16 v[2:5], v[2:5], v[26:29], v[18:21]
	s_waitcnt vmcnt(0)
	s_nop 1
	ds_bpermute_b32 v18, v82, v38
	ds_bpermute_b32 v19, v82, v39
	ds_bpermute_b32 v20, v82, v40
	ds_bpermute_b32 v21, v82, v41
	s_waitcnt lgkmcnt(4)
	v_mfma_f32_16x16x32_bf16 v[14:17], v[14:17], v[26:29], v[22:25]
	s_waitcnt lgkmcnt(0)
	v_mfma_f32_16x16x32_bf16 v[10:13], v[18:21], v[26:29], v[10:13]
	ds_write_b128 v90, v[6:9]
	ds_write_b128 v90, v[2:5] offset:1024
	s_nop 3
	ds_write_b128 v90, v[14:17] offset:2048
	s_nop 0
	ds_write_b128 v90, v[10:13] offset:3072
	v_or_b32_e32 v8, s12, v89
	v_mov_b32_e32 v4, 0
	v_mov_b32_e32 v5, 0
	v_mov_b32_e32 v2, 0
	v_mov_b32_e32 v3, 0
	s_waitcnt lgkmcnt(0)
	s_barrier
	s_cbranch_vccnz .LBB0_1938
	v_add_u32_e32 v2, s14, v83
	v_ashrrev_i32_e32 v3, 31, v2
	v_lshlrev_b64 v[2:3], 11, v[2:3]
	v_lshl_add_u64 v[2:3], s[40:41], 0, v[2:3]
	v_lshlrev_b32_e32 v66, 1, v8
	v_lshl_add_u64 v[2:3], v[2:3], 0, v[66:67]
	global_load_dwordx2 v[6:7], v[2:3], off
	ds_read_b128 v[2:5], v87
	ds_read_b128 v[10:13], v87 offset:4096
	ds_read_b128 v[14:17], v87 offset:8192
	ds_read_b128 v[18:21], v87 offset:12288
	ds_read_b128 v[22:25], v87 offset:16384
	ds_read_b128 v[26:29], v87 offset:20480
	ds_read_b128 v[30:33], v87 offset:24576
	ds_read_b128 v[34:37], v87 offset:28672
	s_waitcnt lgkmcnt(7)
	v_pk_add_f32 v[4:5], v[4:5], 0 op_sel_hi:[1,0]
	v_pk_add_f32 v[2:3], v[2:3], 0 op_sel_hi:[1,0]
	s_waitcnt lgkmcnt(6)
	v_pk_add_f32 v[4:5], v[4:5], v[12:13]
	v_pk_add_f32 v[2:3], v[2:3], v[10:11]
	s_waitcnt lgkmcnt(5)
	v_pk_add_f32 v[4:5], v[4:5], v[16:17]
	v_pk_add_f32 v[2:3], v[2:3], v[14:15]
	s_waitcnt lgkmcnt(4)
	v_pk_add_f32 v[4:5], v[4:5], v[20:21]
	v_pk_add_f32 v[2:3], v[2:3], v[18:19]
	s_waitcnt lgkmcnt(3)
	v_pk_add_f32 v[4:5], v[4:5], v[24:25]
	v_pk_add_f32 v[2:3], v[2:3], v[22:23]
	s_waitcnt lgkmcnt(2)
	v_pk_add_f32 v[4:5], v[4:5], v[28:29]
	v_pk_add_f32 v[2:3], v[2:3], v[26:27]
	s_waitcnt lgkmcnt(1)
	v_pk_add_f32 v[4:5], v[4:5], v[32:33]
	v_pk_add_f32 v[2:3], v[2:3], v[30:31]
	v_and_b32_e32 v38, 64, v92
	s_waitcnt lgkmcnt(0)
	v_pk_add_f32 v[4:5], v[4:5], v[36:37]
	v_pk_add_f32 v[10:11], v[2:3], v[34:35]
	v_xor_b32_e32 v9, 16, v92
	v_add_u32_e32 v38, 64, v38
	v_cmp_lt_i32_e32 vcc, v9, v38
	s_waitcnt vmcnt(0)
	v_lshlrev_b32_e32 v12, 16, v6
	v_and_b32_e32 v13, 0xffff0000, v6
	v_lshlrev_b32_e32 v2, 16, v7
	v_and_b32_e32 v3, 0xffff0000, v7
	v_pk_fma_f32 v[2:3], v[4:5], 0.5, v[2:3] op_sel_hi:[1,0,1]
	v_pk_fma_f32 v[4:5], v[10:11], 0.5, v[12:13] op_sel_hi:[1,0,1]
	v_mul_f32_e32 v7, v3, v3
	v_mul_f32_e32 v6, v5, v5
	v_cndmask_b32_e32 v9, v92, v9, vcc
	v_fmac_f32_e32 v6, v4, v4
	v_fmac_f32_e32 v7, v2, v2
	v_lshlrev_b32_e32 v9, 2, v9
	v_add_f32_e32 v6, v6, v7
	v_mov_b32_e32 v7, v6
	s_nop 1
	v_permlane16_swap_b32_e32 v6, v7
	v_xor_b32_e32 v9, 32, v92
	v_cmp_lt_i32_e32 vcc, v9, v38
	s_waitcnt lgkmcnt(0)
	v_add_f32_e32 v6, v6, v7
	v_cndmask_b32_e32 v9, v92, v9, vcc
	v_lshlrev_b32_e32 v7, 2, v9
	v_mov_b32_e32 v7, v6
	s_nop 1
	v_permlane32_swap_b32_e32 v6, v7
	s_and_saveexec_b64 s[12:13], s[0:1]
	s_cbranch_execz .LBB0_1937
	s_waitcnt lgkmcnt(0)
	v_add_f32_e32 v6, v6, v7
	ds_write_b32 v88, v6 offset:32768
